# bundle1 + peeled first K iteration with SrcC=0 (no accumulator zeroing) in 8 GEMM loops
# speedup vs baseline: 1.0127x; 1.0014x over previous
.LBB0_292:
	s_ashr_i32 s13, s12, 31
	s_lshl_b64 s[14:15], s[12:13], 20
	s_add_u32 s14, s19, s14
	s_addc_u32 s15, s22, s15
	s_and_b64 s[16:17], s[2:3], exec
	s_cselect_b32 s13, s15, s41
	s_cselect_b32 s74, s14, s40
	s_ashr_i32 s11, s10, 31
	s_lshl_b64 s[16:17], s[10:11], 20
	s_add_u32 s16, s23, s16
	s_addc_u32 s17, s28, s17
	s_and_b64 s[54:55], s[2:3], exec
	s_cselect_b32 s11, s17, s43
	s_cselect_b32 s75, s16, s42
	s_add_u32 s40, s40, 0x80080
	s_addc_u32 s41, s41, 0
	s_add_u32 s76, s42, 0x100
	s_addc_u32 s77, s43, 0
	s_mov_b32 s78, -2
	ds_read_b128 v[146:149], v153
	ds_read_b128 v[156:159], v153 offset:1024
	ds_read_b128 v[160:163], v153 offset:2048
	ds_read_b128 v[164:167], v153 offset:3072
	ds_read_b128 v[168:171], v154
	ds_read_b128 v[172:175], v154 offset:1024
	ds_read_b128 v[180:183], v154 offset:2048
	ds_read_b128 v[184:187], v154 offset:3072
	s_add_u32 s42, s40, 0xfff80080
	s_addc_u32 s43, s41, -1
	s_cmp_eq_u32 s78, 28
	s_cselect_b32 s55, s13, s43
	s_cselect_b32 s54, s74, s42
	s_cselect_b32 s43, s11, s77
	s_cselect_b32 s42, s75, s76
	v_lshl_add_u64 v[176:177], s[40:41], 0, v[138:139]
	s_add_i32 m0, s35, 0xc000
	ds_read_b128 v[188:191], v155
	ds_read_b128 v[192:195], v155 offset:1024
	ds_read_b128 v[196:199], v155 offset:2048
	ds_read_b128 v[200:203], v155 offset:3072
	ds_read_b128 v[204:207], v155 offset:4096
	ds_read_b128 v[208:211], v155 offset:5120
	ds_read_b128 v[212:215], v155 offset:6144
	ds_read_b128 v[216:219], v155 offset:7168
	global_load_lds_dwordx4 v[176:177], off
	v_lshl_add_u64 v[176:177], s[40:41], 0, v[140:141]
	s_add_i32 m0, s35, 0xe000
	s_nop 0
	global_load_lds_dwordx4 v[176:177], off
	s_waitcnt vmcnt(8)
	s_waitcnt lgkmcnt(0)
	s_setprio 1
	s_barrier
	v_mfma_f32_16x16x32_bf16 v[126:129], v[146:149], v[188:191], 0
	v_mfma_f32_16x16x32_bf16 v[118:121], v[160:163], v[188:191], 0
	v_mfma_f32_16x16x32_bf16 v[110:113], v[146:149], v[196:199], 0
	v_mfma_f32_16x16x32_bf16 v[102:105], v[160:163], v[196:199], 0
	v_mfma_f32_16x16x32_bf16 v[94:97], v[146:149], v[204:207], 0
	v_mfma_f32_16x16x32_bf16 v[86:89], v[160:163], v[204:207], 0
	v_mfma_f32_16x16x32_bf16 v[78:81], v[146:149], v[212:215], 0
	v_mfma_f32_16x16x32_bf16 v[70:73], v[160:163], v[212:215], 0
	v_mfma_f32_16x16x32_bf16 v[126:129], v[156:159], v[192:195], v[126:129]
	v_mfma_f32_16x16x32_bf16 v[118:121], v[164:167], v[192:195], v[118:121]
	v_mfma_f32_16x16x32_bf16 v[110:113], v[156:159], v[200:203], v[110:113]
	v_mfma_f32_16x16x32_bf16 v[102:105], v[164:167], v[200:203], v[102:105]
	v_mfma_f32_16x16x32_bf16 v[94:97], v[156:159], v[208:211], v[94:97]
	v_mfma_f32_16x16x32_bf16 v[86:89], v[164:167], v[208:211], v[86:89]
	v_mfma_f32_16x16x32_bf16 v[78:81], v[156:159], v[216:219], v[78:81]
	v_mfma_f32_16x16x32_bf16 v[70:73], v[164:167], v[216:219], v[70:73]
	s_setprio 0
	s_setprio 1
	v_mfma_f32_16x16x32_bf16 v[122:125], v[168:171], v[188:191], 0
	v_mfma_f32_16x16x32_bf16 v[114:117], v[180:183], v[188:191], 0
	v_mfma_f32_16x16x32_bf16 v[106:109], v[168:171], v[196:199], 0
	v_mfma_f32_16x16x32_bf16 v[98:101], v[180:183], v[196:199], 0
	v_mfma_f32_16x16x32_bf16 v[90:93], v[168:171], v[204:207], 0
	v_mfma_f32_16x16x32_bf16 v[82:85], v[180:183], v[204:207], 0
	v_mfma_f32_16x16x32_bf16 v[74:77], v[168:171], v[212:215], 0
	v_mfma_f32_16x16x32_bf16 v[66:69], v[180:183], v[212:215], 0
	v_mfma_f32_16x16x32_bf16 v[122:125], v[172:175], v[192:195], v[122:125]
	v_mfma_f32_16x16x32_bf16 v[114:117], v[184:187], v[192:195], v[114:117]
	v_mfma_f32_16x16x32_bf16 v[106:109], v[172:175], v[200:203], v[106:109]
	v_mfma_f32_16x16x32_bf16 v[98:101], v[184:187], v[200:203], v[98:101]
	v_mfma_f32_16x16x32_bf16 v[90:93], v[172:175], v[208:211], v[90:93]
	v_mfma_f32_16x16x32_bf16 v[82:85], v[184:187], v[208:211], v[82:85]
	v_mfma_f32_16x16x32_bf16 v[74:77], v[172:175], v[216:219], v[74:77]
	v_mfma_f32_16x16x32_bf16 v[66:69], v[184:187], v[216:219], v[66:69]
	s_barrier
	s_setprio 0
	s_add_i32 s79, s70, s29
	v_lshl_add_u64 v[176:177], s[42:43], 0, v[134:135]
	s_mov_b32 m0, s79
	ds_read_b128 v[188:191], v155 offset:16384
	ds_read_b128 v[192:195], v155 offset:17408
	ds_read_b128 v[196:199], v155 offset:18432
	ds_read_b128 v[200:203], v155 offset:19456
	ds_read_b128 v[204:207], v155 offset:20480
	ds_read_b128 v[208:211], v155 offset:21504
	ds_read_b128 v[212:215], v155 offset:22528
	ds_read_b128 v[216:219], v155 offset:23552
	global_load_lds_dwordx4 v[176:177], off
	s_add_i32 m0, s79, 0x2000
	s_add_u32 s80, s42, 0x80000
	v_lshl_add_u64 v[220:221], s[42:43], 0, v[130:131]
	s_addc_u32 s81, s43, 0
	s_add_i32 s79, s71, s29
	global_load_lds_dwordx4 v[220:221], off
	v_lshl_add_u64 v[222:223], s[80:81], 0, v[134:135]
	s_mov_b32 m0, s79
	v_lshl_add_u64 v[224:225], s[54:55], 0, v[132:133]
	global_load_lds_dwordx4 v[222:223], off
	v_lshl_add_u64 v[222:223], s[80:81], 0, v[130:131]
	s_add_i32 m0, s79, 0x2000
	s_nop 0
	global_load_lds_dwordx4 v[222:223], off
	v_lshl_add_u64 v[222:223], s[54:55], 0, v[136:137]
	s_mov_b32 m0, s35
	s_nop 0
	global_load_lds_dwordx4 v[222:223], off
	s_mov_b32 m0, s57
	s_nop 0
	global_load_lds_dwordx4 v[224:225], off
	s_waitcnt vmcnt(8)
	s_waitcnt lgkmcnt(0)
	s_setprio 1
	s_barrier
	v_mfma_f32_16x16x32_bf16 v[62:65], v[146:149], v[188:191], 0
	v_mfma_f32_16x16x32_bf16 v[54:57], v[160:163], v[188:191], 0
	v_mfma_f32_16x16x32_bf16 v[46:49], v[146:149], v[196:199], 0
	v_mfma_f32_16x16x32_bf16 v[38:41], v[160:163], v[196:199], 0
	v_mfma_f32_16x16x32_bf16 v[30:33], v[146:149], v[204:207], 0
	v_mfma_f32_16x16x32_bf16 v[22:25], v[160:163], v[204:207], 0
	v_mfma_f32_16x16x32_bf16 v[14:17], v[146:149], v[212:215], 0
	v_mfma_f32_16x16x32_bf16 v[6:9], v[160:163], v[212:215], 0
	v_mfma_f32_16x16x32_bf16 v[62:65], v[156:159], v[192:195], v[62:65]
	v_mfma_f32_16x16x32_bf16 v[54:57], v[164:167], v[192:195], v[54:57]
	v_mfma_f32_16x16x32_bf16 v[46:49], v[156:159], v[200:203], v[46:49]
	v_mfma_f32_16x16x32_bf16 v[38:41], v[164:167], v[200:203], v[38:41]
	v_mfma_f32_16x16x32_bf16 v[30:33], v[156:159], v[208:211], v[30:33]
	v_mfma_f32_16x16x32_bf16 v[22:25], v[164:167], v[208:211], v[22:25]
	v_mfma_f32_16x16x32_bf16 v[14:17], v[156:159], v[216:219], v[14:17]
	v_mfma_f32_16x16x32_bf16 v[6:9], v[164:167], v[216:219], v[6:9]
	s_setprio 0
	s_setprio 1
	v_mfma_f32_16x16x32_bf16 v[58:61], v[168:171], v[188:191], 0
	v_mfma_f32_16x16x32_bf16 v[50:53], v[180:183], v[188:191], 0
	v_mfma_f32_16x16x32_bf16 v[42:45], v[168:171], v[196:199], 0
	v_mfma_f32_16x16x32_bf16 v[34:37], v[180:183], v[196:199], 0
	v_mfma_f32_16x16x32_bf16 v[26:29], v[168:171], v[204:207], 0
	v_mfma_f32_16x16x32_bf16 v[18:21], v[180:183], v[204:207], 0
	v_mfma_f32_16x16x32_bf16 v[10:13], v[168:171], v[212:215], 0
	v_mfma_f32_16x16x32_bf16 v[2:5], v[180:183], v[212:215], 0
	v_mfma_f32_16x16x32_bf16 v[58:61], v[172:175], v[192:195], v[58:61]
	v_mfma_f32_16x16x32_bf16 v[50:53], v[184:187], v[192:195], v[50:53]
	v_mfma_f32_16x16x32_bf16 v[42:45], v[172:175], v[200:203], v[42:45]
	v_mfma_f32_16x16x32_bf16 v[34:37], v[184:187], v[200:203], v[34:37]
	v_mfma_f32_16x16x32_bf16 v[26:29], v[172:175], v[208:211], v[26:29]
	v_mfma_f32_16x16x32_bf16 v[18:21], v[184:187], v[208:211], v[18:21]
	v_mfma_f32_16x16x32_bf16 v[10:13], v[172:175], v[216:219], v[10:13]
	v_mfma_f32_16x16x32_bf16 v[2:5], v[184:187], v[216:219], v[2:5]
	s_barrier
	s_setprio 0
	s_add_i32 s79, 0, 0x18000
	v_add_u32_e32 v1, s79, v151
	s_add_i32 s80, 0, 0x1c000
	ds_read_b128 v[146:149], v1
	ds_read_b128 v[156:159], v1 offset:1024
	ds_read_b128 v[160:163], v1 offset:2048
	ds_read_b128 v[164:167], v1 offset:3072
	v_add_u32_e32 v1, s80, v151
	ds_read_b128 v[168:171], v1
	ds_read_b128 v[172:175], v1 offset:1024
	ds_read_b128 v[180:183], v1 offset:2048
	ds_read_b128 v[184:187], v1 offset:3072
	s_add_u32 s54, s54, 0x80000
	s_addc_u32 s55, s55, 0
	s_mov_b32 m0, s58
	v_lshl_add_u64 v[226:227], s[54:55], 0, v[136:137]
	ds_read_b128 v[188:191], v155 offset:32768
	ds_read_b128 v[192:195], v155 offset:33792
	ds_read_b128 v[196:199], v155 offset:34816
	ds_read_b128 v[200:203], v155 offset:35840
	ds_read_b128 v[204:207], v155 offset:36864
	ds_read_b128 v[208:211], v155 offset:37888
	ds_read_b128 v[212:215], v155 offset:38912
	ds_read_b128 v[216:219], v155 offset:39936
	global_load_lds_dwordx4 v[226:227], off
	v_lshl_add_u64 v[226:227], s[54:55], 0, v[132:133]
	s_mov_b32 m0, s59
	s_nop 0
	global_load_lds_dwordx4 v[226:227], off
	s_waitcnt vmcnt(8)
	s_waitcnt lgkmcnt(0)
	s_setprio 1
	s_barrier
	v_mfma_f32_16x16x32_bf16 v[126:129], v[146:149], v[188:191], v[126:129]
	v_mfma_f32_16x16x32_bf16 v[118:121], v[160:163], v[188:191], v[118:121]
	v_mfma_f32_16x16x32_bf16 v[110:113], v[146:149], v[196:199], v[110:113]
	v_mfma_f32_16x16x32_bf16 v[102:105], v[160:163], v[196:199], v[102:105]
	v_mfma_f32_16x16x32_bf16 v[94:97], v[146:149], v[204:207], v[94:97]
	v_mfma_f32_16x16x32_bf16 v[86:89], v[160:163], v[204:207], v[86:89]
	v_mfma_f32_16x16x32_bf16 v[78:81], v[146:149], v[212:215], v[78:81]
	v_mfma_f32_16x16x32_bf16 v[70:73], v[160:163], v[212:215], v[70:73]
	v_mfma_f32_16x16x32_bf16 v[126:129], v[156:159], v[192:195], v[126:129]
	v_mfma_f32_16x16x32_bf16 v[118:121], v[164:167], v[192:195], v[118:121]
	v_mfma_f32_16x16x32_bf16 v[110:113], v[156:159], v[200:203], v[110:113]
	v_mfma_f32_16x16x32_bf16 v[102:105], v[164:167], v[200:203], v[102:105]
	v_mfma_f32_16x16x32_bf16 v[94:97], v[156:159], v[208:211], v[94:97]
	v_mfma_f32_16x16x32_bf16 v[86:89], v[164:167], v[208:211], v[86:89]
	v_mfma_f32_16x16x32_bf16 v[78:81], v[156:159], v[216:219], v[78:81]
	v_mfma_f32_16x16x32_bf16 v[70:73], v[164:167], v[216:219], v[70:73]
	s_setprio 0
	s_setprio 1
	v_mfma_f32_16x16x32_bf16 v[122:125], v[168:171], v[188:191], v[122:125]
	v_mfma_f32_16x16x32_bf16 v[114:117], v[180:183], v[188:191], v[114:117]
	v_mfma_f32_16x16x32_bf16 v[106:109], v[168:171], v[196:199], v[106:109]
	v_mfma_f32_16x16x32_bf16 v[98:101], v[180:183], v[196:199], v[98:101]
	v_mfma_f32_16x16x32_bf16 v[90:93], v[168:171], v[204:207], v[90:93]
	v_mfma_f32_16x16x32_bf16 v[82:85], v[180:183], v[204:207], v[82:85]
	v_mfma_f32_16x16x32_bf16 v[74:77], v[168:171], v[212:215], v[74:77]
	v_mfma_f32_16x16x32_bf16 v[66:69], v[180:183], v[212:215], v[66:69]
	v_mfma_f32_16x16x32_bf16 v[122:125], v[172:175], v[192:195], v[122:125]
	v_mfma_f32_16x16x32_bf16 v[114:117], v[184:187], v[192:195], v[114:117]
	v_mfma_f32_16x16x32_bf16 v[106:109], v[172:175], v[200:203], v[106:109]
	v_mfma_f32_16x16x32_bf16 v[98:101], v[184:187], v[200:203], v[98:101]
	v_mfma_f32_16x16x32_bf16 v[90:93], v[172:175], v[208:211], v[90:93]
	v_mfma_f32_16x16x32_bf16 v[82:85], v[184:187], v[208:211], v[82:85]
	v_mfma_f32_16x16x32_bf16 v[74:77], v[172:175], v[216:219], v[74:77]
	v_mfma_f32_16x16x32_bf16 v[66:69], v[184:187], v[216:219], v[66:69]
	s_barrier
	s_setprio 0
	s_add_i32 s54, s79, s29
	v_lshl_add_u64 v[176:177], v[176:177], 0, s[6:7]
	s_mov_b32 m0, s54
	ds_read_b128 v[188:191], v155 offset:49152
	ds_read_b128 v[192:195], v155 offset:50176
	ds_read_b128 v[196:199], v155 offset:51200
	ds_read_b128 v[200:203], v155 offset:52224
	ds_read_b128 v[204:207], v155 offset:53248
	ds_read_b128 v[208:211], v155 offset:54272
	ds_read_b128 v[212:215], v155 offset:55296
	ds_read_b128 v[216:219], v155 offset:56320
	global_load_lds_dwordx4 v[176:177], off
	s_add_i32 m0, s54, 0x2000
	s_add_u32 s42, s42, 0x80080
	v_lshl_add_u64 v[176:177], v[220:221], 0, s[6:7]
	s_addc_u32 s43, s43, 0
	s_add_i32 s54, s80, s29
	global_load_lds_dwordx4 v[176:177], off
	v_lshl_add_u64 v[176:177], s[42:43], 0, v[134:135]
	s_mov_b32 m0, s54
	s_nop 0
	global_load_lds_dwordx4 v[176:177], off
	v_lshl_add_u64 v[176:177], s[42:43], 0, v[130:131]
	s_add_i32 m0, s54, 0x2000
	s_nop 0
	global_load_lds_dwordx4 v[176:177], off
	v_lshl_add_u64 v[176:177], v[222:223], 0, s[6:7]
	s_mov_b32 m0, s64
	s_nop 0
	global_load_lds_dwordx4 v[176:177], off
	v_lshl_add_u64 v[176:177], v[224:225], 0, s[6:7]
	s_mov_b32 m0, s65
	s_nop 0
	global_load_lds_dwordx4 v[176:177], off
	s_waitcnt vmcnt(8)
	s_waitcnt lgkmcnt(0)
	s_setprio 1
	s_barrier
	v_mfma_f32_16x16x32_bf16 v[62:65], v[146:149], v[188:191], v[62:65]
	v_mfma_f32_16x16x32_bf16 v[54:57], v[160:163], v[188:191], v[54:57]
	v_mfma_f32_16x16x32_bf16 v[46:49], v[146:149], v[196:199], v[46:49]
	v_mfma_f32_16x16x32_bf16 v[38:41], v[160:163], v[196:199], v[38:41]
	v_mfma_f32_16x16x32_bf16 v[30:33], v[146:149], v[204:207], v[30:33]
	v_mfma_f32_16x16x32_bf16 v[22:25], v[160:163], v[204:207], v[22:25]
	v_mfma_f32_16x16x32_bf16 v[14:17], v[146:149], v[212:215], v[14:17]
	v_mfma_f32_16x16x32_bf16 v[6:9], v[160:163], v[212:215], v[6:9]
	v_mfma_f32_16x16x32_bf16 v[62:65], v[156:159], v[192:195], v[62:65]
	v_mfma_f32_16x16x32_bf16 v[54:57], v[164:167], v[192:195], v[54:57]
	v_mfma_f32_16x16x32_bf16 v[46:49], v[156:159], v[200:203], v[46:49]
	v_mfma_f32_16x16x32_bf16 v[38:41], v[164:167], v[200:203], v[38:41]
	v_mfma_f32_16x16x32_bf16 v[30:33], v[156:159], v[208:211], v[30:33]
	v_mfma_f32_16x16x32_bf16 v[22:25], v[164:167], v[208:211], v[22:25]
	v_mfma_f32_16x16x32_bf16 v[14:17], v[156:159], v[216:219], v[14:17]
	v_mfma_f32_16x16x32_bf16 v[6:9], v[164:167], v[216:219], v[6:9]
	s_setprio 0
	s_setprio 1
	v_mfma_f32_16x16x32_bf16 v[58:61], v[168:171], v[188:191], v[58:61]
	v_mfma_f32_16x16x32_bf16 v[50:53], v[180:183], v[188:191], v[50:53]
	v_mfma_f32_16x16x32_bf16 v[42:45], v[168:171], v[196:199], v[42:45]
	v_mfma_f32_16x16x32_bf16 v[34:37], v[180:183], v[196:199], v[34:37]
	v_mfma_f32_16x16x32_bf16 v[26:29], v[168:171], v[204:207], v[26:29]
	v_mfma_f32_16x16x32_bf16 v[18:21], v[180:183], v[204:207], v[18:21]
	v_mfma_f32_16x16x32_bf16 v[10:13], v[168:171], v[212:215], v[10:13]
	v_mfma_f32_16x16x32_bf16 v[2:5], v[180:183], v[212:215], v[2:5]
	v_mfma_f32_16x16x32_bf16 v[58:61], v[172:175], v[192:195], v[58:61]
	v_mfma_f32_16x16x32_bf16 v[50:53], v[184:187], v[192:195], v[50:53]
	v_mfma_f32_16x16x32_bf16 v[42:45], v[172:175], v[200:203], v[42:45]
	v_mfma_f32_16x16x32_bf16 v[34:37], v[184:187], v[200:203], v[34:37]
	v_mfma_f32_16x16x32_bf16 v[26:29], v[172:175], v[208:211], v[26:29]
	v_mfma_f32_16x16x32_bf16 v[18:21], v[184:187], v[208:211], v[18:21]
	v_mfma_f32_16x16x32_bf16 v[10:13], v[172:175], v[216:219], v[10:13]
	v_mfma_f32_16x16x32_bf16 v[2:5], v[184:187], v[216:219], v[2:5]
	s_barrier
	s_setprio 0
	s_add_i32 s78, s78, 2
	s_add_u32 s40, s40, 0x100
	s_addc_u32 s41, s41, 0
	s_add_u32 s76, s76, 0x100
	s_addc_u32 s77, s77, 0
	s_cmp_gt_u32 s78, 29

.LBB0_378:
	s_add_u32 s12, s58, 0x160080
	s_addc_u32 s13, s59, 0
	s_add_u32 s81, s56, 0x100
	s_addc_u32 s82, s57, 0
	s_mov_b32 s83, -2
	ds_read_b128 v[130:133], v208
	ds_read_b128 v[134:137], v208 offset:1024
	ds_read_b128 v[138:141], v208 offset:2048
	ds_read_b128 v[142:145], v208 offset:3072
	ds_read_b128 v[146:149], v209
	ds_read_b128 v[150:153], v209 offset:1024
	ds_read_b128 v[154:157], v209 offset:2048
	ds_read_b128 v[158:161], v209 offset:3072
	s_add_u32 s56, s12, 0xffea0080
	s_addc_u32 s57, s13, -1
	s_cmpk_eq_i32 s83, 0x54
	s_cselect_b32 s59, s43, s57
	s_cselect_b32 s58, s42, s56
	s_cselect_b32 s57, s55, s82
	s_cselect_b32 s56, s54, s81
	v_lshl_add_u64 v[204:205], s[12:13], 0, v[188:189]
	s_add_i32 m0, s31, 0xc000
	ds_read_b128 v[162:165], v210
	ds_read_b128 v[166:169], v210 offset:1024
	ds_read_b128 v[170:173], v210 offset:2048
	ds_read_b128 v[174:177], v210 offset:3072
	ds_read_b128 v[196:199], v210 offset:4096
	ds_read_b128 v[200:203], v210 offset:5120
	ds_read_b128 v[212:215], v210 offset:6144
	ds_read_b128 v[216:219], v210 offset:7168
	global_load_lds_dwordx4 v[204:205], off
	v_lshl_add_u64 v[204:205], s[12:13], 0, v[190:191]
	s_add_i32 m0, s31, 0xe000
	s_nop 0
	global_load_lds_dwordx4 v[204:205], off
	s_waitcnt vmcnt(8)
	s_waitcnt lgkmcnt(0)
	s_setprio 1
	s_barrier
	v_mfma_f32_16x16x32_bf16 v[126:129], v[130:133], v[162:165], 0
	v_mfma_f32_16x16x32_bf16 v[122:125], v[138:141], v[162:165], 0
	v_mfma_f32_16x16x32_bf16 v[110:113], v[130:133], v[170:173], 0
	v_mfma_f32_16x16x32_bf16 v[106:109], v[138:141], v[170:173], 0
	v_mfma_f32_16x16x32_bf16 v[94:97], v[130:133], v[196:199], 0
	v_mfma_f32_16x16x32_bf16 v[90:93], v[138:141], v[196:199], 0
	v_mfma_f32_16x16x32_bf16 v[78:81], v[130:133], v[212:215], 0
	v_mfma_f32_16x16x32_bf16 v[74:77], v[138:141], v[212:215], 0
	v_mfma_f32_16x16x32_bf16 v[126:129], v[134:137], v[166:169], v[126:129]
	v_mfma_f32_16x16x32_bf16 v[122:125], v[142:145], v[166:169], v[122:125]
	v_mfma_f32_16x16x32_bf16 v[110:113], v[134:137], v[174:177], v[110:113]
	v_mfma_f32_16x16x32_bf16 v[106:109], v[142:145], v[174:177], v[106:109]
	v_mfma_f32_16x16x32_bf16 v[94:97], v[134:137], v[200:203], v[94:97]
	v_mfma_f32_16x16x32_bf16 v[90:93], v[142:145], v[200:203], v[90:93]
	v_mfma_f32_16x16x32_bf16 v[78:81], v[134:137], v[216:219], v[78:81]
	v_mfma_f32_16x16x32_bf16 v[74:77], v[142:145], v[216:219], v[74:77]
	s_setprio 0
	s_setprio 1
	v_mfma_f32_16x16x32_bf16 v[118:121], v[146:149], v[162:165], 0
	v_mfma_f32_16x16x32_bf16 v[114:117], v[154:157], v[162:165], 0
	v_mfma_f32_16x16x32_bf16 v[102:105], v[146:149], v[170:173], 0
	v_mfma_f32_16x16x32_bf16 v[98:101], v[154:157], v[170:173], 0
	v_mfma_f32_16x16x32_bf16 v[86:89], v[146:149], v[196:199], 0
	v_mfma_f32_16x16x32_bf16 v[82:85], v[154:157], v[196:199], 0
	v_mfma_f32_16x16x32_bf16 v[70:73], v[146:149], v[212:215], 0
	v_mfma_f32_16x16x32_bf16 v[66:69], v[154:157], v[212:215], 0
	v_mfma_f32_16x16x32_bf16 v[118:121], v[150:153], v[166:169], v[118:121]
	v_mfma_f32_16x16x32_bf16 v[114:117], v[158:161], v[166:169], v[114:117]
	v_mfma_f32_16x16x32_bf16 v[102:105], v[150:153], v[174:177], v[102:105]
	v_mfma_f32_16x16x32_bf16 v[98:101], v[158:161], v[174:177], v[98:101]
	v_mfma_f32_16x16x32_bf16 v[86:89], v[150:153], v[200:203], v[86:89]
	v_mfma_f32_16x16x32_bf16 v[82:85], v[158:161], v[200:203], v[82:85]
	v_mfma_f32_16x16x32_bf16 v[70:73], v[150:153], v[216:219], v[70:73]
	v_mfma_f32_16x16x32_bf16 v[66:69], v[158:161], v[216:219], v[66:69]
	s_barrier
	s_setprio 0
	s_add_i32 s85, s75, s29
	v_lshl_add_u64 v[204:205], s[56:57], 0, v[182:183]
	s_mov_b32 m0, s85
	ds_read_b128 v[162:165], v210 offset:16384
	ds_read_b128 v[166:169], v210 offset:17408
	ds_read_b128 v[170:173], v210 offset:18432
	ds_read_b128 v[174:177], v210 offset:19456
	ds_read_b128 v[196:199], v210 offset:20480
	ds_read_b128 v[200:203], v210 offset:21504
	ds_read_b128 v[212:215], v210 offset:22528
	ds_read_b128 v[216:219], v210 offset:23552
	global_load_lds_dwordx4 v[204:205], off
	s_add_i32 m0, s85, 0x2000
	s_add_u32 s88, s56, 0x160000
	v_lshl_add_u64 v[220:221], s[56:57], 0, v[186:187]
	s_addc_u32 s89, s57, 0
	s_add_i32 s85, s76, s29
	global_load_lds_dwordx4 v[220:221], off
	v_lshl_add_u64 v[222:223], s[88:89], 0, v[182:183]
	s_mov_b32 m0, s85
	v_lshl_add_u64 v[224:225], s[58:59], 0, v[184:185]
	global_load_lds_dwordx4 v[222:223], off
	v_lshl_add_u64 v[222:223], s[88:89], 0, v[186:187]
	s_add_i32 m0, s85, 0x2000
	s_nop 0
	global_load_lds_dwordx4 v[222:223], off
	v_lshl_add_u64 v[222:223], s[58:59], 0, v[180:181]
	s_mov_b32 m0, s31
	s_nop 0
	global_load_lds_dwordx4 v[222:223], off
	s_mov_b32 m0, s64
	s_nop 0
	global_load_lds_dwordx4 v[224:225], off
	s_waitcnt vmcnt(8)
	s_waitcnt lgkmcnt(0)
	s_setprio 1
	s_barrier
	v_mfma_f32_16x16x32_bf16 v[62:65], v[130:133], v[162:165], 0
	v_mfma_f32_16x16x32_bf16 v[58:61], v[138:141], v[162:165], 0
	v_mfma_f32_16x16x32_bf16 v[46:49], v[130:133], v[170:173], 0
	v_mfma_f32_16x16x32_bf16 v[42:45], v[138:141], v[170:173], 0
	v_mfma_f32_16x16x32_bf16 v[30:33], v[130:133], v[196:199], 0
	v_mfma_f32_16x16x32_bf16 v[26:29], v[138:141], v[196:199], 0
	v_mfma_f32_16x16x32_bf16 v[14:17], v[130:133], v[212:215], 0
	v_mfma_f32_16x16x32_bf16 v[10:13], v[138:141], v[212:215], 0
	v_mfma_f32_16x16x32_bf16 v[62:65], v[134:137], v[166:169], v[62:65]
	v_mfma_f32_16x16x32_bf16 v[58:61], v[142:145], v[166:169], v[58:61]
	v_mfma_f32_16x16x32_bf16 v[46:49], v[134:137], v[174:177], v[46:49]
	v_mfma_f32_16x16x32_bf16 v[42:45], v[142:145], v[174:177], v[42:45]
	v_mfma_f32_16x16x32_bf16 v[30:33], v[134:137], v[200:203], v[30:33]
	v_mfma_f32_16x16x32_bf16 v[26:29], v[142:145], v[200:203], v[26:29]
	v_mfma_f32_16x16x32_bf16 v[14:17], v[134:137], v[216:219], v[14:17]
	v_mfma_f32_16x16x32_bf16 v[10:13], v[142:145], v[216:219], v[10:13]
	s_setprio 0
	s_setprio 1
	v_mfma_f32_16x16x32_bf16 v[54:57], v[146:149], v[162:165], 0
	v_mfma_f32_16x16x32_bf16 v[50:53], v[154:157], v[162:165], 0
	v_mfma_f32_16x16x32_bf16 v[38:41], v[146:149], v[170:173], 0
	v_mfma_f32_16x16x32_bf16 v[34:37], v[154:157], v[170:173], 0
	v_mfma_f32_16x16x32_bf16 v[22:25], v[146:149], v[196:199], 0
	v_mfma_f32_16x16x32_bf16 v[18:21], v[154:157], v[196:199], 0
	v_mfma_f32_16x16x32_bf16 v[6:9], v[146:149], v[212:215], 0
	v_mfma_f32_16x16x32_bf16 v[2:5], v[154:157], v[212:215], 0
	v_mfma_f32_16x16x32_bf16 v[54:57], v[150:153], v[166:169], v[54:57]
	v_mfma_f32_16x16x32_bf16 v[50:53], v[158:161], v[166:169], v[50:53]
	v_mfma_f32_16x16x32_bf16 v[38:41], v[150:153], v[174:177], v[38:41]
	v_mfma_f32_16x16x32_bf16 v[34:37], v[158:161], v[174:177], v[34:37]
	v_mfma_f32_16x16x32_bf16 v[22:25], v[150:153], v[200:203], v[22:25]
	v_mfma_f32_16x16x32_bf16 v[18:21], v[158:161], v[200:203], v[18:21]
	v_mfma_f32_16x16x32_bf16 v[6:9], v[150:153], v[216:219], v[6:9]
	v_mfma_f32_16x16x32_bf16 v[2:5], v[158:161], v[216:219], v[2:5]
	s_barrier
	s_setprio 0
	s_add_i32 s85, 0, 0x18000
	v_add_u32_e32 v1, s85, v206
	s_add_i32 s87, 0, 0x1c000
	ds_read_b128 v[130:133], v1
	ds_read_b128 v[134:137], v1 offset:1024
	ds_read_b128 v[138:141], v1 offset:2048
	ds_read_b128 v[142:145], v1 offset:3072
	v_add_u32_e32 v1, s87, v206
	ds_read_b128 v[146:149], v1
	ds_read_b128 v[150:153], v1 offset:1024
	ds_read_b128 v[154:157], v1 offset:2048
	ds_read_b128 v[158:161], v1 offset:3072
	s_add_u32 s58, s58, 0x160000
	s_addc_u32 s59, s59, 0
	s_mov_b32 m0, s65
	v_lshl_add_u64 v[226:227], s[58:59], 0, v[180:181]
	ds_read_b128 v[162:165], v210 offset:32768
	ds_read_b128 v[166:169], v210 offset:33792
	ds_read_b128 v[170:173], v210 offset:34816
	ds_read_b128 v[174:177], v210 offset:35840
	ds_read_b128 v[196:199], v210 offset:36864
	ds_read_b128 v[200:203], v210 offset:37888
	ds_read_b128 v[212:215], v210 offset:38912
	ds_read_b128 v[216:219], v210 offset:39936
	global_load_lds_dwordx4 v[226:227], off
	v_lshl_add_u64 v[226:227], s[58:59], 0, v[184:185]
	s_mov_b32 m0, s66
	s_nop 0
	global_load_lds_dwordx4 v[226:227], off
	s_waitcnt vmcnt(8)
	s_waitcnt lgkmcnt(0)
	s_setprio 1
	s_barrier
	v_mfma_f32_16x16x32_bf16 v[126:129], v[130:133], v[162:165], v[126:129]
	v_mfma_f32_16x16x32_bf16 v[122:125], v[138:141], v[162:165], v[122:125]
	v_mfma_f32_16x16x32_bf16 v[110:113], v[130:133], v[170:173], v[110:113]
	v_mfma_f32_16x16x32_bf16 v[106:109], v[138:141], v[170:173], v[106:109]
	v_mfma_f32_16x16x32_bf16 v[94:97], v[130:133], v[196:199], v[94:97]
	v_mfma_f32_16x16x32_bf16 v[90:93], v[138:141], v[196:199], v[90:93]
	v_mfma_f32_16x16x32_bf16 v[78:81], v[130:133], v[212:215], v[78:81]
	v_mfma_f32_16x16x32_bf16 v[74:77], v[138:141], v[212:215], v[74:77]
	v_mfma_f32_16x16x32_bf16 v[126:129], v[134:137], v[166:169], v[126:129]
	v_mfma_f32_16x16x32_bf16 v[122:125], v[142:145], v[166:169], v[122:125]
	v_mfma_f32_16x16x32_bf16 v[110:113], v[134:137], v[174:177], v[110:113]
	v_mfma_f32_16x16x32_bf16 v[106:109], v[142:145], v[174:177], v[106:109]
	v_mfma_f32_16x16x32_bf16 v[94:97], v[134:137], v[200:203], v[94:97]
	v_mfma_f32_16x16x32_bf16 v[90:93], v[142:145], v[200:203], v[90:93]
	v_mfma_f32_16x16x32_bf16 v[78:81], v[134:137], v[216:219], v[78:81]
	v_mfma_f32_16x16x32_bf16 v[74:77], v[142:145], v[216:219], v[74:77]
	s_setprio 0
	s_setprio 1
	v_mfma_f32_16x16x32_bf16 v[118:121], v[146:149], v[162:165], v[118:121]
	v_mfma_f32_16x16x32_bf16 v[114:117], v[154:157], v[162:165], v[114:117]
	v_mfma_f32_16x16x32_bf16 v[102:105], v[146:149], v[170:173], v[102:105]
	v_mfma_f32_16x16x32_bf16 v[98:101], v[154:157], v[170:173], v[98:101]
	v_mfma_f32_16x16x32_bf16 v[86:89], v[146:149], v[196:199], v[86:89]
	v_mfma_f32_16x16x32_bf16 v[82:85], v[154:157], v[196:199], v[82:85]
	v_mfma_f32_16x16x32_bf16 v[70:73], v[146:149], v[212:215], v[70:73]
	v_mfma_f32_16x16x32_bf16 v[66:69], v[154:157], v[212:215], v[66:69]
	v_mfma_f32_16x16x32_bf16 v[118:121], v[150:153], v[166:169], v[118:121]
	v_mfma_f32_16x16x32_bf16 v[114:117], v[158:161], v[166:169], v[114:117]
	v_mfma_f32_16x16x32_bf16 v[102:105], v[150:153], v[174:177], v[102:105]
	v_mfma_f32_16x16x32_bf16 v[98:101], v[158:161], v[174:177], v[98:101]
	v_mfma_f32_16x16x32_bf16 v[86:89], v[150:153], v[200:203], v[86:89]
	v_mfma_f32_16x16x32_bf16 v[82:85], v[158:161], v[200:203], v[82:85]
	v_mfma_f32_16x16x32_bf16 v[70:73], v[150:153], v[216:219], v[70:73]
	v_mfma_f32_16x16x32_bf16 v[66:69], v[158:161], v[216:219], v[66:69]
	s_barrier
	s_setprio 0
	s_add_i32 s58, s85, s29
	v_lshl_add_u64 v[204:205], v[204:205], 0, s[16:17]
	s_mov_b32 m0, s58
	ds_read_b128 v[162:165], v210 offset:49152
	ds_read_b128 v[166:169], v210 offset:50176
	ds_read_b128 v[170:173], v210 offset:51200
	ds_read_b128 v[174:177], v210 offset:52224
	ds_read_b128 v[196:199], v210 offset:53248
	ds_read_b128 v[200:203], v210 offset:54272
	ds_read_b128 v[212:215], v210 offset:55296
	ds_read_b128 v[216:219], v210 offset:56320
	global_load_lds_dwordx4 v[204:205], off
	s_add_i32 m0, s58, 0x2000
	s_add_u32 s56, s56, 0x160080
	v_lshl_add_u64 v[204:205], v[220:221], 0, s[16:17]
	s_addc_u32 s57, s57, 0
	s_add_i32 s58, s87, s29
	global_load_lds_dwordx4 v[204:205], off
	v_lshl_add_u64 v[204:205], s[56:57], 0, v[182:183]
	s_mov_b32 m0, s58
	s_nop 0
	global_load_lds_dwordx4 v[204:205], off
	v_lshl_add_u64 v[204:205], s[56:57], 0, v[186:187]
	s_add_i32 m0, s58, 0x2000
	s_nop 0
	global_load_lds_dwordx4 v[204:205], off
	v_lshl_add_u64 v[204:205], v[222:223], 0, s[16:17]
	s_mov_b32 m0, s71
	s_nop 0
	global_load_lds_dwordx4 v[204:205], off
	v_lshl_add_u64 v[204:205], v[224:225], 0, s[16:17]
	s_mov_b32 m0, s72
	s_nop 0
	global_load_lds_dwordx4 v[204:205], off
	s_waitcnt vmcnt(8)
	s_waitcnt lgkmcnt(0)
	s_setprio 1
	s_barrier
	v_mfma_f32_16x16x32_bf16 v[62:65], v[130:133], v[162:165], v[62:65]
	v_mfma_f32_16x16x32_bf16 v[58:61], v[138:141], v[162:165], v[58:61]
	v_mfma_f32_16x16x32_bf16 v[46:49], v[130:133], v[170:173], v[46:49]
	v_mfma_f32_16x16x32_bf16 v[42:45], v[138:141], v[170:173], v[42:45]
	v_mfma_f32_16x16x32_bf16 v[30:33], v[130:133], v[196:199], v[30:33]
	v_mfma_f32_16x16x32_bf16 v[26:29], v[138:141], v[196:199], v[26:29]
	v_mfma_f32_16x16x32_bf16 v[14:17], v[130:133], v[212:215], v[14:17]
	v_mfma_f32_16x16x32_bf16 v[10:13], v[138:141], v[212:215], v[10:13]
	v_mfma_f32_16x16x32_bf16 v[62:65], v[134:137], v[166:169], v[62:65]
	v_mfma_f32_16x16x32_bf16 v[58:61], v[142:145], v[166:169], v[58:61]
	v_mfma_f32_16x16x32_bf16 v[46:49], v[134:137], v[174:177], v[46:49]
	v_mfma_f32_16x16x32_bf16 v[42:45], v[142:145], v[174:177], v[42:45]
	v_mfma_f32_16x16x32_bf16 v[30:33], v[134:137], v[200:203], v[30:33]
	v_mfma_f32_16x16x32_bf16 v[26:29], v[142:145], v[200:203], v[26:29]
	v_mfma_f32_16x16x32_bf16 v[14:17], v[134:137], v[216:219], v[14:17]
	v_mfma_f32_16x16x32_bf16 v[10:13], v[142:145], v[216:219], v[10:13]
	s_setprio 0
	s_setprio 1
	v_mfma_f32_16x16x32_bf16 v[54:57], v[146:149], v[162:165], v[54:57]
	v_mfma_f32_16x16x32_bf16 v[50:53], v[154:157], v[162:165], v[50:53]
	v_mfma_f32_16x16x32_bf16 v[38:41], v[146:149], v[170:173], v[38:41]
	v_mfma_f32_16x16x32_bf16 v[34:37], v[154:157], v[170:173], v[34:37]
	v_mfma_f32_16x16x32_bf16 v[22:25], v[146:149], v[196:199], v[22:25]
	v_mfma_f32_16x16x32_bf16 v[18:21], v[154:157], v[196:199], v[18:21]
	v_mfma_f32_16x16x32_bf16 v[6:9], v[146:149], v[212:215], v[6:9]
	v_mfma_f32_16x16x32_bf16 v[2:5], v[154:157], v[212:215], v[2:5]
	v_mfma_f32_16x16x32_bf16 v[54:57], v[150:153], v[166:169], v[54:57]
	v_mfma_f32_16x16x32_bf16 v[50:53], v[158:161], v[166:169], v[50:53]
	v_mfma_f32_16x16x32_bf16 v[38:41], v[150:153], v[174:177], v[38:41]
	v_mfma_f32_16x16x32_bf16 v[34:37], v[158:161], v[174:177], v[34:37]
	v_mfma_f32_16x16x32_bf16 v[22:25], v[150:153], v[200:203], v[22:25]
	v_mfma_f32_16x16x32_bf16 v[18:21], v[158:161], v[200:203], v[18:21]
	v_mfma_f32_16x16x32_bf16 v[6:9], v[150:153], v[216:219], v[6:9]
	v_mfma_f32_16x16x32_bf16 v[2:5], v[158:161], v[216:219], v[2:5]
	s_barrier
	s_setprio 0
	s_add_i32 s83, s83, 2
	s_add_u32 s12, s12, 0x100
	s_addc_u32 s13, s13, 0
	s_add_u32 s81, s81, 0x100
	s_addc_u32 s82, s82, 0
	s_cmpk_gt_u32 s83, 0x55

.LBB0_468:
	s_ashr_i32 s11, s10, 31
	s_lshl_b64 s[70:71], s[10:11], 20
	s_add_u32 s70, s89, s70
	s_addc_u32 s71, s90, s71
	s_and_b64 s[72:73], s[4:5], exec
	s_cselect_b32 s11, s71, s1
	s_cselect_b32 s76, s70, s0
	s_ashr_i32 s69, s68, 31
	s_lshl_b64 s[72:73], s[68:69], 20
	s_add_u32 s72, s91, s72
	s_addc_u32 s73, s92, s73
	s_and_b64 s[74:75], s[4:5], exec
	s_cselect_b32 s69, s73, s9
	s_cselect_b32 s77, s72, s8
	s_add_u32 s0, s0, 0x80080
	s_addc_u32 s1, s1, 0
	s_add_u32 s78, s8, 0x100
	s_addc_u32 s79, s9, 0
	s_mov_b32 s80, -2
	ds_read_b128 v[78:81], v204
	ds_read_b128 v[138:141], v204 offset:1024
	ds_read_b128 v[142:145], v204 offset:2048
	ds_read_b128 v[146:149], v204 offset:3072
	ds_read_b128 v[170:173], v205
	ds_read_b128 v[174:177], v205 offset:1024
	ds_read_b128 v[180:183], v205 offset:2048
	ds_read_b128 v[210:213], v205 offset:3072
	s_add_u32 s8, s0, 0xfff80080
	s_addc_u32 s9, s1, -1
	s_cmp_eq_u32 s80, 28
	s_cselect_b32 s75, s11, s9
	s_cselect_b32 s74, s76, s8
	s_cselect_b32 s9, s69, s79
	s_cselect_b32 s8, s77, s78
	v_lshl_add_u64 v[246:247], s[0:1], 0, v[162:163]
	s_add_i32 m0, s94, 0xc000
	ds_read_b128 v[214:217], v206
	ds_read_b128 v[218:221], v206 offset:1024
	ds_read_b128 v[222:225], v206 offset:2048
	ds_read_b128 v[226:229], v206 offset:3072
	ds_read_b128 v[230:233], v206 offset:4096
	ds_read_b128 v[234:237], v206 offset:5120
	ds_read_b128 v[238:241], v206 offset:6144
	ds_read_b128 v[242:245], v206 offset:7168
	global_load_lds_dwordx4 v[246:247], off
	v_lshl_add_u64 v[246:247], s[0:1], 0, v[164:165]
	s_add_i32 m0, s94, 0xe000
	s_nop 0
	global_load_lds_dwordx4 v[246:247], off
	s_waitcnt vmcnt(8)
	s_waitcnt lgkmcnt(0)
	s_setprio 1
	s_barrier
	v_mfma_f32_16x16x32_bf16 v[66:69], v[78:81], v[214:217], 0
	v_mfma_f32_16x16x32_bf16 v[62:65], v[142:145], v[214:217], 0
	v_mfma_f32_16x16x32_bf16 v[58:61], v[78:81], v[222:225], 0
	v_mfma_f32_16x16x32_bf16 v[54:57], v[142:145], v[222:225], 0
	v_mfma_f32_16x16x32_bf16 v[46:49], v[78:81], v[230:233], 0
	v_mfma_f32_16x16x32_bf16 v[42:45], v[142:145], v[230:233], 0
	v_mfma_f32_16x16x32_bf16 v[38:41], v[78:81], v[238:241], 0
	v_mfma_f32_16x16x32_bf16 v[34:37], v[142:145], v[238:241], 0
	v_mfma_f32_16x16x32_bf16 v[66:69], v[138:141], v[218:221], v[66:69]
	v_mfma_f32_16x16x32_bf16 v[62:65], v[146:149], v[218:221], v[62:65]
	v_mfma_f32_16x16x32_bf16 v[58:61], v[138:141], v[226:229], v[58:61]
	v_mfma_f32_16x16x32_bf16 v[54:57], v[146:149], v[226:229], v[54:57]
	v_mfma_f32_16x16x32_bf16 v[46:49], v[138:141], v[234:237], v[46:49]
	v_mfma_f32_16x16x32_bf16 v[42:45], v[146:149], v[234:237], v[42:45]
	v_mfma_f32_16x16x32_bf16 v[38:41], v[138:141], v[242:245], v[38:41]
	v_mfma_f32_16x16x32_bf16 v[34:37], v[146:149], v[242:245], v[34:37]
	s_setprio 0
	s_setprio 1
	v_mfma_f32_16x16x32_bf16 v[134:137], v[170:173], v[214:217], 0
	v_mfma_f32_16x16x32_bf16 v[130:133], v[180:183], v[214:217], 0
	v_mfma_f32_16x16x32_bf16 v[126:129], v[170:173], v[222:225], 0
	v_mfma_f32_16x16x32_bf16 v[122:125], v[180:183], v[222:225], 0
	v_mfma_f32_16x16x32_bf16 v[118:121], v[170:173], v[230:233], 0
	v_mfma_f32_16x16x32_bf16 v[114:117], v[180:183], v[230:233], 0
	v_mfma_f32_16x16x32_bf16 v[110:113], v[170:173], v[238:241], 0
	v_mfma_f32_16x16x32_bf16 v[106:109], v[180:183], v[238:241], 0
	v_mfma_f32_16x16x32_bf16 v[134:137], v[174:177], v[218:221], v[134:137]
	v_mfma_f32_16x16x32_bf16 v[130:133], v[210:213], v[218:221], v[130:133]
	v_mfma_f32_16x16x32_bf16 v[126:129], v[174:177], v[226:229], v[126:129]
	v_mfma_f32_16x16x32_bf16 v[122:125], v[210:213], v[226:229], v[122:125]
	v_mfma_f32_16x16x32_bf16 v[118:121], v[174:177], v[234:237], v[118:121]
	v_mfma_f32_16x16x32_bf16 v[114:117], v[210:213], v[234:237], v[114:117]
	v_mfma_f32_16x16x32_bf16 v[110:113], v[174:177], v[242:245], v[110:113]
	v_mfma_f32_16x16x32_bf16 v[106:109], v[210:213], v[242:245], v[106:109]
	s_barrier
	s_setprio 0
	s_add_i32 s81, s53, s93
	v_lshl_add_u64 v[246:247], s[8:9], 0, v[152:153]
	s_mov_b32 m0, s81
	ds_read_b128 v[214:217], v206 offset:16384
	ds_read_b128 v[218:221], v206 offset:17408
	ds_read_b128 v[222:225], v206 offset:18432
	ds_read_b128 v[226:229], v206 offset:19456
	ds_read_b128 v[230:233], v206 offset:20480
	ds_read_b128 v[234:237], v206 offset:21504
	ds_read_b128 v[238:241], v206 offset:22528
	ds_read_b128 v[242:245], v206 offset:23552
	global_load_lds_dwordx4 v[246:247], off
	s_add_i32 m0, s81, 0x2000
	s_add_u32 s82, s8, 0x80000
	v_lshl_add_u64 v[248:249], s[8:9], 0, v[156:157]
	s_addc_u32 s83, s9, 0
	s_add_i32 s81, s54, s93
	global_load_lds_dwordx4 v[248:249], off
	v_lshl_add_u64 v[250:251], s[82:83], 0, v[152:153]
	s_mov_b32 m0, s81
	v_lshl_add_u64 v[252:253], s[74:75], 0, v[154:155]
	global_load_lds_dwordx4 v[250:251], off
	v_lshl_add_u64 v[250:251], s[82:83], 0, v[156:157]
	s_add_i32 m0, s81, 0x2000
	s_nop 0
	global_load_lds_dwordx4 v[250:251], off
	v_lshl_add_u64 v[250:251], s[74:75], 0, v[150:151]
	s_mov_b32 m0, s94
	s_nop 0
	global_load_lds_dwordx4 v[250:251], off
	s_mov_b32 m0, s95
	s_nop 0
	global_load_lds_dwordx4 v[252:253], off
	s_waitcnt vmcnt(8)
	s_waitcnt lgkmcnt(0)
	s_setprio 1
	s_barrier
	v_mfma_f32_16x16x32_bf16 v[30:33], v[78:81], v[214:217], 0
	v_mfma_f32_16x16x32_bf16 v[26:29], v[142:145], v[214:217], 0
	v_mfma_f32_16x16x32_bf16 v[22:25], v[78:81], v[222:225], 0
	v_mfma_f32_16x16x32_bf16 v[18:21], v[142:145], v[222:225], 0
	v_mfma_f32_16x16x32_bf16 v[14:17], v[78:81], v[230:233], 0
	v_mfma_f32_16x16x32_bf16 v[10:13], v[142:145], v[230:233], 0
	v_mfma_f32_16x16x32_bf16 v[6:9], v[78:81], v[238:241], 0
	v_mfma_f32_16x16x32_bf16 v[2:5], v[142:145], v[238:241], 0
	v_mfma_f32_16x16x32_bf16 v[30:33], v[138:141], v[218:221], v[30:33]
	v_mfma_f32_16x16x32_bf16 v[26:29], v[146:149], v[218:221], v[26:29]
	v_mfma_f32_16x16x32_bf16 v[22:25], v[138:141], v[226:229], v[22:25]
	v_mfma_f32_16x16x32_bf16 v[18:21], v[146:149], v[226:229], v[18:21]
	v_mfma_f32_16x16x32_bf16 v[14:17], v[138:141], v[234:237], v[14:17]
	v_mfma_f32_16x16x32_bf16 v[10:13], v[146:149], v[234:237], v[10:13]
	v_mfma_f32_16x16x32_bf16 v[6:9], v[138:141], v[242:245], v[6:9]
	v_mfma_f32_16x16x32_bf16 v[2:5], v[146:149], v[242:245], v[2:5]
	s_setprio 0
	s_setprio 1
	v_mfma_f32_16x16x32_bf16 v[98:101], v[180:183], v[214:217], 0
	v_mfma_f32_16x16x32_bf16 v[94:97], v[170:173], v[222:225], 0
	v_mfma_f32_16x16x32_bf16 v[90:93], v[180:183], v[222:225], 0
	v_mfma_f32_16x16x32_bf16 v[86:89], v[170:173], v[230:233], 0
	v_mfma_f32_16x16x32_bf16 v[82:85], v[180:183], v[230:233], 0
	v_mfma_f32_16x16x32_bf16 v[74:77], v[170:173], v[238:241], 0
	v_mfma_f32_16x16x32_bf16 v[70:73], v[180:183], v[238:241], 0
	v_mfma_f32_16x16x32_bf16 v[78:81], v[170:173], v[214:217], 0
	v_mfma_f32_16x16x32_bf16 v[98:101], v[210:213], v[218:221], v[98:101]
	v_mfma_f32_16x16x32_bf16 v[94:97], v[174:177], v[226:229], v[94:97]
	v_mfma_f32_16x16x32_bf16 v[90:93], v[210:213], v[226:229], v[90:93]
	v_mfma_f32_16x16x32_bf16 v[86:89], v[174:177], v[234:237], v[86:89]
	v_mfma_f32_16x16x32_bf16 v[82:85], v[210:213], v[234:237], v[82:85]
	v_mfma_f32_16x16x32_bf16 v[74:77], v[174:177], v[242:245], v[74:77]
	v_mfma_f32_16x16x32_bf16 v[70:73], v[210:213], v[242:245], v[70:73]
	v_mfma_f32_16x16x32_bf16 v[78:81], v[174:177], v[218:221], v[78:81]
	s_barrier
	s_setprio 0
	s_add_i32 s81, 0, 0x18000
	v_add_u32_e32 v1, s81, v194
	s_add_i32 s82, 0, 0x1c000
	ds_read_b128 v[102:105], v1
	ds_read_b128 v[138:141], v1 offset:1024
	ds_read_b128 v[142:145], v1 offset:2048
	ds_read_b128 v[146:149], v1 offset:3072
	v_add_u32_e32 v1, s82, v194
	ds_read_b128 v[170:173], v1
	ds_read_b128 v[174:177], v1 offset:1024
	ds_read_b128 v[180:183], v1 offset:2048
	ds_read_b128 v[210:213], v1 offset:3072
	s_add_u32 s74, s74, 0x80000
	s_addc_u32 s75, s75, 0
	s_mov_b32 m0, s96
	v_lshl_add_u64 v[190:191], s[74:75], 0, v[150:151]
	ds_read_b128 v[214:217], v206 offset:32768
	ds_read_b128 v[218:221], v206 offset:33792
	ds_read_b128 v[222:225], v206 offset:34816
	ds_read_b128 v[226:229], v206 offset:35840
	ds_read_b128 v[230:233], v206 offset:36864
	ds_read_b128 v[234:237], v206 offset:37888
	ds_read_b128 v[238:241], v206 offset:38912
	ds_read_b128 v[242:245], v206 offset:39936
	global_load_lds_dwordx4 v[190:191], off
	v_lshl_add_u64 v[190:191], s[74:75], 0, v[154:155]
	s_mov_b32 m0, s97
	s_nop 0
	global_load_lds_dwordx4 v[190:191], off
	s_waitcnt vmcnt(8)
	s_waitcnt lgkmcnt(0)
	s_setprio 1
	s_barrier
	v_mfma_f32_16x16x32_bf16 v[66:69], v[102:105], v[214:217], v[66:69]
	v_mfma_f32_16x16x32_bf16 v[62:65], v[142:145], v[214:217], v[62:65]
	v_mfma_f32_16x16x32_bf16 v[58:61], v[102:105], v[222:225], v[58:61]
	v_mfma_f32_16x16x32_bf16 v[54:57], v[142:145], v[222:225], v[54:57]
	v_mfma_f32_16x16x32_bf16 v[46:49], v[102:105], v[230:233], v[46:49]
	v_mfma_f32_16x16x32_bf16 v[42:45], v[142:145], v[230:233], v[42:45]
	v_mfma_f32_16x16x32_bf16 v[38:41], v[102:105], v[238:241], v[38:41]
	v_mfma_f32_16x16x32_bf16 v[34:37], v[142:145], v[238:241], v[34:37]
	v_mfma_f32_16x16x32_bf16 v[66:69], v[138:141], v[218:221], v[66:69]
	v_mfma_f32_16x16x32_bf16 v[62:65], v[146:149], v[218:221], v[62:65]
	v_mfma_f32_16x16x32_bf16 v[58:61], v[138:141], v[226:229], v[58:61]
	v_mfma_f32_16x16x32_bf16 v[54:57], v[146:149], v[226:229], v[54:57]
	v_mfma_f32_16x16x32_bf16 v[46:49], v[138:141], v[234:237], v[46:49]
	v_mfma_f32_16x16x32_bf16 v[42:45], v[146:149], v[234:237], v[42:45]
	v_mfma_f32_16x16x32_bf16 v[38:41], v[138:141], v[242:245], v[38:41]
	v_mfma_f32_16x16x32_bf16 v[34:37], v[146:149], v[242:245], v[34:37]
	s_setprio 0
	s_setprio 1
	v_mfma_f32_16x16x32_bf16 v[134:137], v[170:173], v[214:217], v[134:137]
	v_mfma_f32_16x16x32_bf16 v[130:133], v[180:183], v[214:217], v[130:133]
	v_mfma_f32_16x16x32_bf16 v[126:129], v[170:173], v[222:225], v[126:129]
	v_mfma_f32_16x16x32_bf16 v[122:125], v[180:183], v[222:225], v[122:125]
	v_mfma_f32_16x16x32_bf16 v[118:121], v[170:173], v[230:233], v[118:121]
	v_mfma_f32_16x16x32_bf16 v[114:117], v[180:183], v[230:233], v[114:117]
	v_mfma_f32_16x16x32_bf16 v[110:113], v[170:173], v[238:241], v[110:113]
	v_mfma_f32_16x16x32_bf16 v[106:109], v[180:183], v[238:241], v[106:109]
	v_mfma_f32_16x16x32_bf16 v[134:137], v[174:177], v[218:221], v[134:137]
	v_mfma_f32_16x16x32_bf16 v[130:133], v[210:213], v[218:221], v[130:133]
	v_mfma_f32_16x16x32_bf16 v[126:129], v[174:177], v[226:229], v[126:129]
	v_mfma_f32_16x16x32_bf16 v[122:125], v[210:213], v[226:229], v[122:125]
	v_mfma_f32_16x16x32_bf16 v[118:121], v[174:177], v[234:237], v[118:121]
	v_mfma_f32_16x16x32_bf16 v[114:117], v[210:213], v[234:237], v[114:117]
	v_mfma_f32_16x16x32_bf16 v[110:113], v[174:177], v[242:245], v[110:113]
	v_mfma_f32_16x16x32_bf16 v[106:109], v[210:213], v[242:245], v[106:109]
	s_barrier
	s_setprio 0
	s_add_i32 s74, s81, s93
	v_lshl_add_u64 v[190:191], v[246:247], 0, s[56:57]
	s_mov_b32 m0, s74
	ds_read_b128 v[214:217], v206 offset:49152
	ds_read_b128 v[218:221], v206 offset:50176
	ds_read_b128 v[222:225], v206 offset:51200
	ds_read_b128 v[226:229], v206 offset:52224
	ds_read_b128 v[230:233], v206 offset:53248
	ds_read_b128 v[234:237], v206 offset:54272
	ds_read_b128 v[238:241], v206 offset:55296
	ds_read_b128 v[242:245], v206 offset:56320
	global_load_lds_dwordx4 v[190:191], off
	s_add_i32 m0, s74, 0x2000
	s_add_u32 s8, s8, 0x80080
	v_lshl_add_u64 v[190:191], v[248:249], 0, s[56:57]
	s_addc_u32 s9, s9, 0
	s_add_i32 s74, s82, s93
	global_load_lds_dwordx4 v[190:191], off
	v_lshl_add_u64 v[190:191], s[8:9], 0, v[152:153]
	s_mov_b32 m0, s74
	s_nop 0
	global_load_lds_dwordx4 v[190:191], off
	v_lshl_add_u64 v[190:191], s[8:9], 0, v[156:157]
	s_add_i32 m0, s74, 0x2000
	s_nop 0
	global_load_lds_dwordx4 v[190:191], off
	v_lshl_add_u64 v[190:191], v[250:251], 0, s[56:57]
	s_mov_b32 m0, s85
	s_nop 0
	global_load_lds_dwordx4 v[190:191], off
	v_lshl_add_u64 v[190:191], v[252:253], 0, s[56:57]
	s_mov_b32 m0, s18
	s_nop 0
	global_load_lds_dwordx4 v[190:191], off
	s_waitcnt vmcnt(8)
	s_waitcnt lgkmcnt(0)
	s_setprio 1
	s_barrier
	v_mfma_f32_16x16x32_bf16 v[30:33], v[102:105], v[214:217], v[30:33]
	v_mfma_f32_16x16x32_bf16 v[26:29], v[142:145], v[214:217], v[26:29]
	v_mfma_f32_16x16x32_bf16 v[22:25], v[102:105], v[222:225], v[22:25]
	v_mfma_f32_16x16x32_bf16 v[18:21], v[142:145], v[222:225], v[18:21]
	v_mfma_f32_16x16x32_bf16 v[14:17], v[102:105], v[230:233], v[14:17]
	v_mfma_f32_16x16x32_bf16 v[10:13], v[142:145], v[230:233], v[10:13]
	v_mfma_f32_16x16x32_bf16 v[6:9], v[102:105], v[238:241], v[6:9]
	v_mfma_f32_16x16x32_bf16 v[2:5], v[142:145], v[238:241], v[2:5]
	v_mfma_f32_16x16x32_bf16 v[30:33], v[138:141], v[218:221], v[30:33]
	v_mfma_f32_16x16x32_bf16 v[26:29], v[146:149], v[218:221], v[26:29]
	v_mfma_f32_16x16x32_bf16 v[22:25], v[138:141], v[226:229], v[22:25]
	v_mfma_f32_16x16x32_bf16 v[18:21], v[146:149], v[226:229], v[18:21]
	v_mfma_f32_16x16x32_bf16 v[14:17], v[138:141], v[234:237], v[14:17]
	v_mfma_f32_16x16x32_bf16 v[10:13], v[146:149], v[234:237], v[10:13]
	v_mfma_f32_16x16x32_bf16 v[6:9], v[138:141], v[242:245], v[6:9]
	v_mfma_f32_16x16x32_bf16 v[2:5], v[146:149], v[242:245], v[2:5]
	s_setprio 0
	s_setprio 1
	v_mfma_f32_16x16x32_bf16 v[78:81], v[170:173], v[214:217], v[78:81]
	v_mfma_f32_16x16x32_bf16 v[102:105], v[174:177], v[218:221], v[78:81]
	v_mfma_f32_16x16x32_bf16 v[78:81], v[180:183], v[214:217], v[98:101]
	v_mfma_f32_16x16x32_bf16 v[98:101], v[210:213], v[218:221], v[78:81]
	v_mfma_f32_16x16x32_bf16 v[78:81], v[170:173], v[222:225], v[94:97]
	v_mfma_f32_16x16x32_bf16 v[94:97], v[174:177], v[226:229], v[78:81]
	v_mfma_f32_16x16x32_bf16 v[78:81], v[180:183], v[222:225], v[90:93]
	v_mfma_f32_16x16x32_bf16 v[90:93], v[210:213], v[226:229], v[78:81]
	v_mfma_f32_16x16x32_bf16 v[78:81], v[170:173], v[230:233], v[86:89]
	v_mfma_f32_16x16x32_bf16 v[86:89], v[174:177], v[234:237], v[78:81]
	v_mfma_f32_16x16x32_bf16 v[78:81], v[180:183], v[230:233], v[82:85]
	v_mfma_f32_16x16x32_bf16 v[74:77], v[170:173], v[238:241], v[74:77]
	v_mfma_f32_16x16x32_bf16 v[70:73], v[180:183], v[238:241], v[70:73]
	v_mfma_f32_16x16x32_bf16 v[82:85], v[210:213], v[234:237], v[78:81]
	v_mfma_f32_16x16x32_bf16 v[74:77], v[174:177], v[242:245], v[74:77]
	v_mfma_f32_16x16x32_bf16 v[70:73], v[210:213], v[242:245], v[70:73]
	s_barrier
	s_setprio 0
	s_add_i32 s80, s80, 2
	s_add_u32 s0, s0, 0x100
	s_addc_u32 s1, s1, 0
	s_add_u32 s78, s78, 0x100
	s_addc_u32 s79, s79, 0
	s_cmp_gt_u32 s80, 29

.LBB0_700:
	s_ashr_i32 s37, s36, 31
	s_lshl_b64 s[40:41], s[36:37], 20
	s_add_u32 s40, s18, s40
	s_addc_u32 s41, s19, s41
	s_and_b64 s[42:43], s[16:17], exec
	s_cselect_b32 s37, s41, s55
	s_cselect_b32 s75, s40, s54
	s_ashr_i32 s35, s34, 31
	s_lshl_b64 s[42:43], s[34:35], 20
	s_add_u32 s42, s28, s42
	s_addc_u32 s43, s29, s43
	s_and_b64 s[58:59], s[16:17], exec
	s_cselect_b32 s35, s43, s57
	s_cselect_b32 s76, s42, s56
	s_add_u32 s54, s54, 0x80080
	s_addc_u32 s55, s55, 0
	s_add_u32 s77, s56, 0x100
	s_addc_u32 s78, s57, 0
	s_mov_b32 s79, -2
	ds_read_b128 v[144:147], v141
	ds_read_b128 v[158:161], v141 offset:1024
	ds_read_b128 v[162:165], v141 offset:2048
	ds_read_b128 v[166:169], v141 offset:3072
	ds_read_b128 v[170:173], v142
	ds_read_b128 v[174:177], v142 offset:1024
	ds_read_b128 v[180:183], v142 offset:2048
	ds_read_b128 v[190:193], v142 offset:3072
	s_add_u32 s56, s54, 0xfff80080
	s_addc_u32 s57, s55, -1
	s_cmp_eq_u32 s79, 28
	s_cselect_b32 s59, s37, s57
	s_cselect_b32 s58, s75, s56
	s_cselect_b32 s57, s35, s78
	s_cselect_b32 s56, s76, s77
	v_lshl_add_u64 v[134:135], s[54:55], 0, v[130:131]
	s_add_i32 m0, s53, 0xc000
	ds_read_b128 v[194:197], v143
	ds_read_b128 v[198:201], v143 offset:1024
	ds_read_b128 v[202:205], v143 offset:2048
	ds_read_b128 v[206:209], v143 offset:3072
	ds_read_b128 v[210:213], v143 offset:4096
	ds_read_b128 v[214:217], v143 offset:5120
	ds_read_b128 v[218:221], v143 offset:6144
	ds_read_b128 v[222:225], v143 offset:7168
	global_load_lds_dwordx4 v[134:135], off
	v_lshl_add_u64 v[134:135], s[54:55], 0, v[132:133]
	s_add_i32 m0, s53, 0xe000
	s_nop 0
	global_load_lds_dwordx4 v[134:135], off
	s_waitcnt vmcnt(8)
	s_waitcnt lgkmcnt(0)
	s_setprio 1
	s_barrier
	v_mfma_f32_16x16x32_bf16 v[126:129], v[144:147], v[194:197], 0
	v_mfma_f32_16x16x32_bf16 v[122:125], v[162:165], v[194:197], 0
	v_mfma_f32_16x16x32_bf16 v[114:117], v[144:147], v[202:205], 0
	v_mfma_f32_16x16x32_bf16 v[106:109], v[162:165], v[202:205], 0
	v_mfma_f32_16x16x32_bf16 v[98:101], v[144:147], v[210:213], 0
	v_mfma_f32_16x16x32_bf16 v[90:93], v[162:165], v[210:213], 0
	v_mfma_f32_16x16x32_bf16 v[82:85], v[144:147], v[218:221], 0
	v_mfma_f32_16x16x32_bf16 v[74:77], v[162:165], v[218:221], 0
	v_mfma_f32_16x16x32_bf16 v[126:129], v[158:161], v[198:201], v[126:129]
	v_mfma_f32_16x16x32_bf16 v[122:125], v[166:169], v[198:201], v[122:125]
	v_mfma_f32_16x16x32_bf16 v[114:117], v[158:161], v[206:209], v[114:117]
	v_mfma_f32_16x16x32_bf16 v[106:109], v[166:169], v[206:209], v[106:109]
	v_mfma_f32_16x16x32_bf16 v[98:101], v[158:161], v[214:217], v[98:101]
	v_mfma_f32_16x16x32_bf16 v[90:93], v[166:169], v[214:217], v[90:93]
	v_mfma_f32_16x16x32_bf16 v[82:85], v[158:161], v[222:225], v[82:85]
	v_mfma_f32_16x16x32_bf16 v[74:77], v[166:169], v[222:225], v[74:77]
	s_setprio 0
	s_setprio 1
	v_mfma_f32_16x16x32_bf16 v[118:121], v[170:173], v[194:197], 0
	v_mfma_f32_16x16x32_bf16 v[110:113], v[180:183], v[194:197], 0
	v_mfma_f32_16x16x32_bf16 v[102:105], v[170:173], v[202:205], 0
	v_mfma_f32_16x16x32_bf16 v[94:97], v[180:183], v[202:205], 0
	v_mfma_f32_16x16x32_bf16 v[86:89], v[170:173], v[210:213], 0
	v_mfma_f32_16x16x32_bf16 v[78:81], v[180:183], v[210:213], 0
	v_mfma_f32_16x16x32_bf16 v[70:73], v[170:173], v[218:221], 0
	v_mfma_f32_16x16x32_bf16 v[66:69], v[180:183], v[218:221], 0
	v_mfma_f32_16x16x32_bf16 v[118:121], v[174:177], v[198:201], v[118:121]
	v_mfma_f32_16x16x32_bf16 v[110:113], v[190:193], v[198:201], v[110:113]
	v_mfma_f32_16x16x32_bf16 v[102:105], v[174:177], v[206:209], v[102:105]
	v_mfma_f32_16x16x32_bf16 v[94:97], v[190:193], v[206:209], v[94:97]
	v_mfma_f32_16x16x32_bf16 v[86:89], v[174:177], v[214:217], v[86:89]
	v_mfma_f32_16x16x32_bf16 v[78:81], v[190:193], v[214:217], v[78:81]
	v_mfma_f32_16x16x32_bf16 v[70:73], v[174:177], v[222:225], v[70:73]
	v_mfma_f32_16x16x32_bf16 v[66:69], v[190:193], v[222:225], v[66:69]
	s_barrier
	s_setprio 0
	s_add_i32 s80, s68, s60
	v_lshl_add_u64 v[134:135], s[56:57], 0, v[152:153]
	s_mov_b32 m0, s80
	ds_read_b128 v[194:197], v143 offset:16384
	ds_read_b128 v[198:201], v143 offset:17408
	ds_read_b128 v[202:205], v143 offset:18432
	ds_read_b128 v[206:209], v143 offset:19456
	ds_read_b128 v[210:213], v143 offset:20480
	ds_read_b128 v[214:217], v143 offset:21504
	ds_read_b128 v[218:221], v143 offset:22528
	ds_read_b128 v[222:225], v143 offset:23552
	global_load_lds_dwordx4 v[134:135], off
	s_add_i32 m0, s80, 0x2000
	s_add_u32 s80, s56, 0x80000
	v_lshl_add_u64 v[148:149], s[56:57], 0, v[156:157]
	s_addc_u32 s81, s57, 0
	s_add_i32 s82, s69, s60
	global_load_lds_dwordx4 v[148:149], off
	v_lshl_add_u64 v[226:227], s[80:81], 0, v[152:153]
	s_mov_b32 m0, s82
	v_lshl_add_u64 v[228:229], s[58:59], 0, v[154:155]
	global_load_lds_dwordx4 v[226:227], off
	v_lshl_add_u64 v[226:227], s[80:81], 0, v[156:157]
	s_add_i32 m0, s82, 0x2000
	s_nop 0
	global_load_lds_dwordx4 v[226:227], off
	v_lshl_add_u64 v[226:227], s[58:59], 0, v[150:151]
	s_mov_b32 m0, s53
	s_nop 0
	global_load_lds_dwordx4 v[226:227], off
	s_mov_b32 m0, s61
	s_nop 0
	global_load_lds_dwordx4 v[228:229], off
	s_waitcnt vmcnt(8)
	s_waitcnt lgkmcnt(0)
	s_setprio 1
	s_barrier
	v_mfma_f32_16x16x32_bf16 v[62:65], v[144:147], v[194:197], 0
	v_mfma_f32_16x16x32_bf16 v[58:61], v[162:165], v[194:197], 0
	v_mfma_f32_16x16x32_bf16 v[50:53], v[144:147], v[202:205], 0
	v_mfma_f32_16x16x32_bf16 v[42:45], v[162:165], v[202:205], 0
	v_mfma_f32_16x16x32_bf16 v[34:37], v[144:147], v[210:213], 0
	v_mfma_f32_16x16x32_bf16 v[26:29], v[162:165], v[210:213], 0
	v_mfma_f32_16x16x32_bf16 v[18:21], v[144:147], v[218:221], 0
	v_mfma_f32_16x16x32_bf16 v[10:13], v[162:165], v[218:221], 0
	v_mfma_f32_16x16x32_bf16 v[62:65], v[158:161], v[198:201], v[62:65]
	v_mfma_f32_16x16x32_bf16 v[58:61], v[166:169], v[198:201], v[58:61]
	v_mfma_f32_16x16x32_bf16 v[50:53], v[158:161], v[206:209], v[50:53]
	v_mfma_f32_16x16x32_bf16 v[42:45], v[166:169], v[206:209], v[42:45]
	v_mfma_f32_16x16x32_bf16 v[34:37], v[158:161], v[214:217], v[34:37]
	v_mfma_f32_16x16x32_bf16 v[26:29], v[166:169], v[214:217], v[26:29]
	v_mfma_f32_16x16x32_bf16 v[18:21], v[158:161], v[222:225], v[18:21]
	v_mfma_f32_16x16x32_bf16 v[10:13], v[166:169], v[222:225], v[10:13]
	s_setprio 0
	s_setprio 1
	v_mfma_f32_16x16x32_bf16 v[54:57], v[170:173], v[194:197], 0
	v_mfma_f32_16x16x32_bf16 v[46:49], v[180:183], v[194:197], 0
	v_mfma_f32_16x16x32_bf16 v[38:41], v[170:173], v[202:205], 0
	v_mfma_f32_16x16x32_bf16 v[30:33], v[180:183], v[202:205], 0
	v_mfma_f32_16x16x32_bf16 v[22:25], v[170:173], v[210:213], 0
	v_mfma_f32_16x16x32_bf16 v[14:17], v[180:183], v[210:213], 0
	v_mfma_f32_16x16x32_bf16 v[6:9], v[170:173], v[218:221], 0
	v_mfma_f32_16x16x32_bf16 v[2:5], v[180:183], v[218:221], 0
	v_mfma_f32_16x16x32_bf16 v[54:57], v[174:177], v[198:201], v[54:57]
	v_mfma_f32_16x16x32_bf16 v[46:49], v[190:193], v[198:201], v[46:49]
	v_mfma_f32_16x16x32_bf16 v[38:41], v[174:177], v[206:209], v[38:41]
	v_mfma_f32_16x16x32_bf16 v[30:33], v[190:193], v[206:209], v[30:33]
	v_mfma_f32_16x16x32_bf16 v[22:25], v[174:177], v[214:217], v[22:25]
	v_mfma_f32_16x16x32_bf16 v[14:17], v[190:193], v[214:217], v[14:17]
	v_mfma_f32_16x16x32_bf16 v[6:9], v[174:177], v[222:225], v[6:9]
	v_mfma_f32_16x16x32_bf16 v[2:5], v[190:193], v[222:225], v[2:5]
	s_barrier
	s_setprio 0
	s_add_i32 s80, 0, 0x18000
	v_add_u32_e32 v1, s80, v139
	s_add_i32 s81, 0, 0x1c000
	ds_read_b128 v[144:147], v1
	ds_read_b128 v[158:161], v1 offset:1024
	ds_read_b128 v[162:165], v1 offset:2048
	ds_read_b128 v[166:169], v1 offset:3072
	v_add_u32_e32 v1, s81, v139
	ds_read_b128 v[170:173], v1
	ds_read_b128 v[174:177], v1 offset:1024
	ds_read_b128 v[180:183], v1 offset:2048
	ds_read_b128 v[190:193], v1 offset:3072
	s_add_u32 s58, s58, 0x80000
	s_addc_u32 s59, s59, 0
	s_mov_b32 m0, s62
	v_lshl_add_u64 v[230:231], s[58:59], 0, v[150:151]
	ds_read_b128 v[194:197], v143 offset:32768
	ds_read_b128 v[198:201], v143 offset:33792
	ds_read_b128 v[202:205], v143 offset:34816
	ds_read_b128 v[206:209], v143 offset:35840
	ds_read_b128 v[210:213], v143 offset:36864
	ds_read_b128 v[214:217], v143 offset:37888
	ds_read_b128 v[218:221], v143 offset:38912
	ds_read_b128 v[222:225], v143 offset:39936
	global_load_lds_dwordx4 v[230:231], off
	v_lshl_add_u64 v[230:231], s[58:59], 0, v[154:155]
	s_mov_b32 m0, s63
	s_nop 0
	global_load_lds_dwordx4 v[230:231], off
	s_waitcnt vmcnt(8)
	s_waitcnt lgkmcnt(0)
	s_setprio 1
	s_barrier
	v_mfma_f32_16x16x32_bf16 v[126:129], v[144:147], v[194:197], v[126:129]
	v_mfma_f32_16x16x32_bf16 v[122:125], v[162:165], v[194:197], v[122:125]
	v_mfma_f32_16x16x32_bf16 v[114:117], v[144:147], v[202:205], v[114:117]
	v_mfma_f32_16x16x32_bf16 v[106:109], v[162:165], v[202:205], v[106:109]
	v_mfma_f32_16x16x32_bf16 v[98:101], v[144:147], v[210:213], v[98:101]
	v_mfma_f32_16x16x32_bf16 v[90:93], v[162:165], v[210:213], v[90:93]
	v_mfma_f32_16x16x32_bf16 v[82:85], v[144:147], v[218:221], v[82:85]
	v_mfma_f32_16x16x32_bf16 v[74:77], v[162:165], v[218:221], v[74:77]
	v_mfma_f32_16x16x32_bf16 v[126:129], v[158:161], v[198:201], v[126:129]
	v_mfma_f32_16x16x32_bf16 v[122:125], v[166:169], v[198:201], v[122:125]
	v_mfma_f32_16x16x32_bf16 v[114:117], v[158:161], v[206:209], v[114:117]
	v_mfma_f32_16x16x32_bf16 v[106:109], v[166:169], v[206:209], v[106:109]
	v_mfma_f32_16x16x32_bf16 v[98:101], v[158:161], v[214:217], v[98:101]
	v_mfma_f32_16x16x32_bf16 v[90:93], v[166:169], v[214:217], v[90:93]
	v_mfma_f32_16x16x32_bf16 v[82:85], v[158:161], v[222:225], v[82:85]
	v_mfma_f32_16x16x32_bf16 v[74:77], v[166:169], v[222:225], v[74:77]
	s_setprio 0
	s_setprio 1
	v_mfma_f32_16x16x32_bf16 v[118:121], v[170:173], v[194:197], v[118:121]
	v_mfma_f32_16x16x32_bf16 v[110:113], v[180:183], v[194:197], v[110:113]
	v_mfma_f32_16x16x32_bf16 v[102:105], v[170:173], v[202:205], v[102:105]
	v_mfma_f32_16x16x32_bf16 v[94:97], v[180:183], v[202:205], v[94:97]
	v_mfma_f32_16x16x32_bf16 v[86:89], v[170:173], v[210:213], v[86:89]
	v_mfma_f32_16x16x32_bf16 v[78:81], v[180:183], v[210:213], v[78:81]
	v_mfma_f32_16x16x32_bf16 v[70:73], v[170:173], v[218:221], v[70:73]
	v_mfma_f32_16x16x32_bf16 v[66:69], v[180:183], v[218:221], v[66:69]
	v_mfma_f32_16x16x32_bf16 v[118:121], v[174:177], v[198:201], v[118:121]
	v_mfma_f32_16x16x32_bf16 v[110:113], v[190:193], v[198:201], v[110:113]
	v_mfma_f32_16x16x32_bf16 v[102:105], v[174:177], v[206:209], v[102:105]
	v_mfma_f32_16x16x32_bf16 v[94:97], v[190:193], v[206:209], v[94:97]
	v_mfma_f32_16x16x32_bf16 v[86:89], v[174:177], v[214:217], v[86:89]
	v_mfma_f32_16x16x32_bf16 v[78:81], v[190:193], v[214:217], v[78:81]
	v_mfma_f32_16x16x32_bf16 v[70:73], v[174:177], v[222:225], v[70:73]
	v_mfma_f32_16x16x32_bf16 v[66:69], v[190:193], v[222:225], v[66:69]
	s_barrier
	s_setprio 0
	s_add_i32 s58, s80, s60
	v_lshl_add_u64 v[134:135], v[134:135], 0, s[4:5]
	s_mov_b32 m0, s58
	ds_read_b128 v[194:197], v143 offset:49152
	ds_read_b128 v[198:201], v143 offset:50176
	ds_read_b128 v[202:205], v143 offset:51200
	ds_read_b128 v[206:209], v143 offset:52224
	ds_read_b128 v[210:213], v143 offset:53248
	ds_read_b128 v[214:217], v143 offset:54272
	ds_read_b128 v[218:221], v143 offset:55296
	ds_read_b128 v[222:225], v143 offset:56320
	global_load_lds_dwordx4 v[134:135], off
	s_add_i32 m0, s58, 0x2000
	s_add_u32 s56, s56, 0x80080
	v_lshl_add_u64 v[134:135], v[148:149], 0, s[4:5]
	s_addc_u32 s57, s57, 0
	s_add_i32 s58, s81, s60
	global_load_lds_dwordx4 v[134:135], off
	v_lshl_add_u64 v[134:135], s[56:57], 0, v[152:153]
	s_mov_b32 m0, s58
	s_nop 0
	global_load_lds_dwordx4 v[134:135], off
	v_lshl_add_u64 v[134:135], s[56:57], 0, v[156:157]
	s_add_i32 m0, s58, 0x2000
	s_nop 0
	global_load_lds_dwordx4 v[134:135], off
	v_lshl_add_u64 v[134:135], v[226:227], 0, s[4:5]
	s_mov_b32 m0, s65
	s_nop 0
	global_load_lds_dwordx4 v[134:135], off
	v_lshl_add_u64 v[134:135], v[228:229], 0, s[4:5]
	s_mov_b32 m0, s66
	s_nop 0
	global_load_lds_dwordx4 v[134:135], off
	s_waitcnt vmcnt(8)
	s_waitcnt lgkmcnt(0)
	s_setprio 1
	s_barrier
	v_mfma_f32_16x16x32_bf16 v[62:65], v[144:147], v[194:197], v[62:65]
	v_mfma_f32_16x16x32_bf16 v[58:61], v[162:165], v[194:197], v[58:61]
	v_mfma_f32_16x16x32_bf16 v[50:53], v[144:147], v[202:205], v[50:53]
	v_mfma_f32_16x16x32_bf16 v[42:45], v[162:165], v[202:205], v[42:45]
	v_mfma_f32_16x16x32_bf16 v[34:37], v[144:147], v[210:213], v[34:37]
	v_mfma_f32_16x16x32_bf16 v[26:29], v[162:165], v[210:213], v[26:29]
	v_mfma_f32_16x16x32_bf16 v[18:21], v[144:147], v[218:221], v[18:21]
	v_mfma_f32_16x16x32_bf16 v[10:13], v[162:165], v[218:221], v[10:13]
	v_mfma_f32_16x16x32_bf16 v[62:65], v[158:161], v[198:201], v[62:65]
	v_mfma_f32_16x16x32_bf16 v[58:61], v[166:169], v[198:201], v[58:61]
	v_mfma_f32_16x16x32_bf16 v[50:53], v[158:161], v[206:209], v[50:53]
	v_mfma_f32_16x16x32_bf16 v[42:45], v[166:169], v[206:209], v[42:45]
	v_mfma_f32_16x16x32_bf16 v[34:37], v[158:161], v[214:217], v[34:37]
	v_mfma_f32_16x16x32_bf16 v[26:29], v[166:169], v[214:217], v[26:29]
	v_mfma_f32_16x16x32_bf16 v[18:21], v[158:161], v[222:225], v[18:21]
	v_mfma_f32_16x16x32_bf16 v[10:13], v[166:169], v[222:225], v[10:13]
	s_setprio 0
	s_setprio 1
	v_mfma_f32_16x16x32_bf16 v[54:57], v[170:173], v[194:197], v[54:57]
	v_mfma_f32_16x16x32_bf16 v[46:49], v[180:183], v[194:197], v[46:49]
	v_mfma_f32_16x16x32_bf16 v[38:41], v[170:173], v[202:205], v[38:41]
	v_mfma_f32_16x16x32_bf16 v[30:33], v[180:183], v[202:205], v[30:33]
	v_mfma_f32_16x16x32_bf16 v[22:25], v[170:173], v[210:213], v[22:25]
	v_mfma_f32_16x16x32_bf16 v[14:17], v[180:183], v[210:213], v[14:17]
	v_mfma_f32_16x16x32_bf16 v[6:9], v[170:173], v[218:221], v[6:9]
	v_mfma_f32_16x16x32_bf16 v[2:5], v[180:183], v[218:221], v[2:5]
	v_mfma_f32_16x16x32_bf16 v[54:57], v[174:177], v[198:201], v[54:57]
	v_mfma_f32_16x16x32_bf16 v[46:49], v[190:193], v[198:201], v[46:49]
	v_mfma_f32_16x16x32_bf16 v[38:41], v[174:177], v[206:209], v[38:41]
	v_mfma_f32_16x16x32_bf16 v[30:33], v[190:193], v[206:209], v[30:33]
	v_mfma_f32_16x16x32_bf16 v[22:25], v[174:177], v[214:217], v[22:25]
	v_mfma_f32_16x16x32_bf16 v[14:17], v[190:193], v[214:217], v[14:17]
	v_mfma_f32_16x16x32_bf16 v[6:9], v[174:177], v[222:225], v[6:9]
	v_mfma_f32_16x16x32_bf16 v[2:5], v[190:193], v[222:225], v[2:5]
	s_barrier
	s_setprio 0
	s_add_i32 s79, s79, 2
	s_add_u32 s54, s54, 0x100
	s_addc_u32 s55, s55, 0
	s_add_u32 s77, s77, 0x100
	s_addc_u32 s78, s78, 0
	s_cmp_gt_u32 s79, 29

.LBB0_724:
	s_ashr_i32 s37, s36, 31
	s_lshl_b64 s[40:41], s[36:37], 20
	s_add_u32 s40, s31, s40
	s_addc_u32 s41, s60, s41
	s_and_b64 s[42:43], s[16:17], exec
	s_cselect_b32 s37, s41, s55
	s_cselect_b32 s76, s40, s54
	s_ashr_i32 s35, s34, 31
	s_lshl_b64 s[42:43], s[34:35], 20
	s_add_u32 s42, s18, s42
	s_addc_u32 s43, s19, s43
	s_and_b64 s[58:59], s[16:17], exec
	s_cselect_b32 s35, s43, s57
	s_cselect_b32 s77, s42, s56
	s_add_u32 s54, s54, 0x80080
	s_addc_u32 s55, s55, 0
	s_add_u32 s78, s56, 0x100
	s_addc_u32 s79, s57, 0
	s_mov_b32 s80, -2
	ds_read_b128 v[142:145], v139
	ds_read_b128 v[146:149], v139 offset:1024
	ds_read_b128 v[158:161], v139 offset:2048
	ds_read_b128 v[162:165], v139 offset:3072
	ds_read_b128 v[166:169], v140
	ds_read_b128 v[170:173], v140 offset:1024
	ds_read_b128 v[174:177], v140 offset:2048
	ds_read_b128 v[180:183], v140 offset:3072
	s_add_u32 s56, s54, 0xfff80080
	s_addc_u32 s57, s55, -1
	s_cmp_eq_u32 s80, 28
	s_cselect_b32 s59, s37, s57
	s_cselect_b32 s58, s76, s56
	s_cselect_b32 s57, s35, s79
	s_cselect_b32 s56, s77, s78
	v_lshl_add_u64 v[134:135], s[54:55], 0, v[130:131]
	s_add_i32 m0, s53, 0xc000
	ds_read_b128 v[184:187], v141
	ds_read_b128 v[188:191], v141 offset:1024
	ds_read_b128 v[192:195], v141 offset:2048
	ds_read_b128 v[196:199], v141 offset:3072
	ds_read_b128 v[200:203], v141 offset:4096
	ds_read_b128 v[204:207], v141 offset:5120
	ds_read_b128 v[208:211], v141 offset:6144
	ds_read_b128 v[212:215], v141 offset:7168
	global_load_lds_dwordx4 v[134:135], off
	v_lshl_add_u64 v[134:135], s[54:55], 0, v[132:133]
	s_add_i32 m0, s53, 0xe000
	s_nop 0
	global_load_lds_dwordx4 v[134:135], off
	s_waitcnt vmcnt(8)
	s_waitcnt lgkmcnt(0)
	s_setprio 1
	s_barrier
	v_mfma_f32_16x16x32_bf16 v[126:129], v[142:145], v[184:187], 0
	v_mfma_f32_16x16x32_bf16 v[122:125], v[158:161], v[184:187], 0
	v_mfma_f32_16x16x32_bf16 v[114:117], v[142:145], v[192:195], 0
	v_mfma_f32_16x16x32_bf16 v[106:109], v[158:161], v[192:195], 0
	v_mfma_f32_16x16x32_bf16 v[98:101], v[142:145], v[200:203], 0
	v_mfma_f32_16x16x32_bf16 v[90:93], v[158:161], v[200:203], 0
	v_mfma_f32_16x16x32_bf16 v[82:85], v[142:145], v[208:211], 0
	v_mfma_f32_16x16x32_bf16 v[74:77], v[158:161], v[208:211], 0
	v_mfma_f32_16x16x32_bf16 v[126:129], v[146:149], v[188:191], v[126:129]
	v_mfma_f32_16x16x32_bf16 v[122:125], v[162:165], v[188:191], v[122:125]
	v_mfma_f32_16x16x32_bf16 v[114:117], v[146:149], v[196:199], v[114:117]
	v_mfma_f32_16x16x32_bf16 v[106:109], v[162:165], v[196:199], v[106:109]
	v_mfma_f32_16x16x32_bf16 v[98:101], v[146:149], v[204:207], v[98:101]
	v_mfma_f32_16x16x32_bf16 v[90:93], v[162:165], v[204:207], v[90:93]
	v_mfma_f32_16x16x32_bf16 v[82:85], v[146:149], v[212:215], v[82:85]
	v_mfma_f32_16x16x32_bf16 v[74:77], v[162:165], v[212:215], v[74:77]
	s_setprio 0
	s_setprio 1
	v_mfma_f32_16x16x32_bf16 v[118:121], v[166:169], v[184:187], 0
	v_mfma_f32_16x16x32_bf16 v[110:113], v[174:177], v[184:187], 0
	v_mfma_f32_16x16x32_bf16 v[102:105], v[166:169], v[192:195], 0
	v_mfma_f32_16x16x32_bf16 v[94:97], v[174:177], v[192:195], 0
	v_mfma_f32_16x16x32_bf16 v[86:89], v[166:169], v[200:203], 0
	v_mfma_f32_16x16x32_bf16 v[78:81], v[174:177], v[200:203], 0
	v_mfma_f32_16x16x32_bf16 v[70:73], v[166:169], v[208:211], 0
	v_mfma_f32_16x16x32_bf16 v[66:69], v[174:177], v[208:211], 0
	v_mfma_f32_16x16x32_bf16 v[118:121], v[170:173], v[188:191], v[118:121]
	v_mfma_f32_16x16x32_bf16 v[110:113], v[180:183], v[188:191], v[110:113]
	v_mfma_f32_16x16x32_bf16 v[102:105], v[170:173], v[196:199], v[102:105]
	v_mfma_f32_16x16x32_bf16 v[94:97], v[180:183], v[196:199], v[94:97]
	v_mfma_f32_16x16x32_bf16 v[86:89], v[170:173], v[204:207], v[86:89]
	v_mfma_f32_16x16x32_bf16 v[78:81], v[180:183], v[204:207], v[78:81]
	v_mfma_f32_16x16x32_bf16 v[70:73], v[170:173], v[212:215], v[70:73]
	v_mfma_f32_16x16x32_bf16 v[66:69], v[180:183], v[212:215], v[66:69]
	s_barrier
	s_setprio 0
	s_add_i32 s81, s69, s61
	v_lshl_add_u64 v[134:135], s[56:57], 0, v[152:153]
	s_mov_b32 m0, s81
	ds_read_b128 v[184:187], v141 offset:16384
	ds_read_b128 v[188:191], v141 offset:17408
	ds_read_b128 v[192:195], v141 offset:18432
	ds_read_b128 v[196:199], v141 offset:19456
	ds_read_b128 v[200:203], v141 offset:20480
	ds_read_b128 v[204:207], v141 offset:21504
	ds_read_b128 v[208:211], v141 offset:22528
	ds_read_b128 v[212:215], v141 offset:23552
	global_load_lds_dwordx4 v[134:135], off
	s_add_i32 m0, s81, 0x2000
	s_add_u32 s82, s56, 0x80000
	v_lshl_add_u64 v[216:217], s[56:57], 0, v[156:157]
	s_addc_u32 s83, s57, 0
	s_add_i32 s81, s70, s61
	global_load_lds_dwordx4 v[216:217], off
	v_lshl_add_u64 v[218:219], s[82:83], 0, v[152:153]
	s_mov_b32 m0, s81
	v_lshl_add_u64 v[220:221], s[58:59], 0, v[154:155]
	global_load_lds_dwordx4 v[218:219], off
	v_lshl_add_u64 v[218:219], s[82:83], 0, v[156:157]
	s_add_i32 m0, s81, 0x2000
	s_nop 0
	global_load_lds_dwordx4 v[218:219], off
	v_lshl_add_u64 v[218:219], s[58:59], 0, v[150:151]
	s_mov_b32 m0, s53
	s_nop 0
	global_load_lds_dwordx4 v[218:219], off
	s_mov_b32 m0, s62
	s_nop 0
	global_load_lds_dwordx4 v[220:221], off
	s_waitcnt vmcnt(8)
	s_waitcnt lgkmcnt(0)
	s_setprio 1
	s_barrier
	v_mfma_f32_16x16x32_bf16 v[62:65], v[142:145], v[184:187], 0
	v_mfma_f32_16x16x32_bf16 v[58:61], v[158:161], v[184:187], 0
	v_mfma_f32_16x16x32_bf16 v[50:53], v[142:145], v[192:195], 0
	v_mfma_f32_16x16x32_bf16 v[42:45], v[158:161], v[192:195], 0
	v_mfma_f32_16x16x32_bf16 v[34:37], v[142:145], v[200:203], 0
	v_mfma_f32_16x16x32_bf16 v[26:29], v[158:161], v[200:203], 0
	v_mfma_f32_16x16x32_bf16 v[18:21], v[142:145], v[208:211], 0
	v_mfma_f32_16x16x32_bf16 v[10:13], v[158:161], v[208:211], 0
	v_mfma_f32_16x16x32_bf16 v[62:65], v[146:149], v[188:191], v[62:65]
	v_mfma_f32_16x16x32_bf16 v[58:61], v[162:165], v[188:191], v[58:61]
	v_mfma_f32_16x16x32_bf16 v[50:53], v[146:149], v[196:199], v[50:53]
	v_mfma_f32_16x16x32_bf16 v[42:45], v[162:165], v[196:199], v[42:45]
	v_mfma_f32_16x16x32_bf16 v[34:37], v[146:149], v[204:207], v[34:37]
	v_mfma_f32_16x16x32_bf16 v[26:29], v[162:165], v[204:207], v[26:29]
	v_mfma_f32_16x16x32_bf16 v[18:21], v[146:149], v[212:215], v[18:21]
	v_mfma_f32_16x16x32_bf16 v[10:13], v[162:165], v[212:215], v[10:13]
	s_setprio 0
	s_setprio 1
	v_mfma_f32_16x16x32_bf16 v[54:57], v[166:169], v[184:187], 0
	v_mfma_f32_16x16x32_bf16 v[46:49], v[174:177], v[184:187], 0
	v_mfma_f32_16x16x32_bf16 v[38:41], v[166:169], v[192:195], 0
	v_mfma_f32_16x16x32_bf16 v[30:33], v[174:177], v[192:195], 0
	v_mfma_f32_16x16x32_bf16 v[22:25], v[166:169], v[200:203], 0
	v_mfma_f32_16x16x32_bf16 v[14:17], v[174:177], v[200:203], 0
	v_mfma_f32_16x16x32_bf16 v[6:9], v[166:169], v[208:211], 0
	v_mfma_f32_16x16x32_bf16 v[2:5], v[174:177], v[208:211], 0
	v_mfma_f32_16x16x32_bf16 v[54:57], v[170:173], v[188:191], v[54:57]
	v_mfma_f32_16x16x32_bf16 v[46:49], v[180:183], v[188:191], v[46:49]
	v_mfma_f32_16x16x32_bf16 v[38:41], v[170:173], v[196:199], v[38:41]
	v_mfma_f32_16x16x32_bf16 v[30:33], v[180:183], v[196:199], v[30:33]
	v_mfma_f32_16x16x32_bf16 v[22:25], v[170:173], v[204:207], v[22:25]
	v_mfma_f32_16x16x32_bf16 v[14:17], v[180:183], v[204:207], v[14:17]
	v_mfma_f32_16x16x32_bf16 v[6:9], v[170:173], v[212:215], v[6:9]
	v_mfma_f32_16x16x32_bf16 v[2:5], v[180:183], v[212:215], v[2:5]
	s_barrier
	s_setprio 0
	s_add_i32 s81, 0, 0x18000
	v_add_u32_e32 v1, s81, v136
	s_add_i32 s82, 0, 0x1c000
	ds_read_b128 v[142:145], v1
	ds_read_b128 v[146:149], v1 offset:1024
	ds_read_b128 v[158:161], v1 offset:2048
	ds_read_b128 v[162:165], v1 offset:3072
	v_add_u32_e32 v1, s82, v136
	ds_read_b128 v[166:169], v1
	ds_read_b128 v[170:173], v1 offset:1024
	ds_read_b128 v[174:177], v1 offset:2048
	ds_read_b128 v[180:183], v1 offset:3072
	s_add_u32 s58, s58, 0x80000
	s_addc_u32 s59, s59, 0
	s_mov_b32 m0, s63
	v_lshl_add_u64 v[222:223], s[58:59], 0, v[150:151]
	ds_read_b128 v[184:187], v141 offset:32768
	ds_read_b128 v[188:191], v141 offset:33792
	ds_read_b128 v[192:195], v141 offset:34816
	ds_read_b128 v[196:199], v141 offset:35840
	ds_read_b128 v[200:203], v141 offset:36864
	ds_read_b128 v[204:207], v141 offset:37888
	ds_read_b128 v[208:211], v141 offset:38912
	ds_read_b128 v[212:215], v141 offset:39936
	global_load_lds_dwordx4 v[222:223], off
	v_lshl_add_u64 v[222:223], s[58:59], 0, v[154:155]
	s_mov_b32 m0, s64
	s_nop 0
	global_load_lds_dwordx4 v[222:223], off
	s_waitcnt vmcnt(8)
	s_waitcnt lgkmcnt(0)
	s_setprio 1
	s_barrier
	v_mfma_f32_16x16x32_bf16 v[126:129], v[142:145], v[184:187], v[126:129]
	v_mfma_f32_16x16x32_bf16 v[122:125], v[158:161], v[184:187], v[122:125]
	v_mfma_f32_16x16x32_bf16 v[114:117], v[142:145], v[192:195], v[114:117]
	v_mfma_f32_16x16x32_bf16 v[106:109], v[158:161], v[192:195], v[106:109]
	v_mfma_f32_16x16x32_bf16 v[98:101], v[142:145], v[200:203], v[98:101]
	v_mfma_f32_16x16x32_bf16 v[90:93], v[158:161], v[200:203], v[90:93]
	v_mfma_f32_16x16x32_bf16 v[82:85], v[142:145], v[208:211], v[82:85]
	v_mfma_f32_16x16x32_bf16 v[74:77], v[158:161], v[208:211], v[74:77]
	v_mfma_f32_16x16x32_bf16 v[126:129], v[146:149], v[188:191], v[126:129]
	v_mfma_f32_16x16x32_bf16 v[122:125], v[162:165], v[188:191], v[122:125]
	v_mfma_f32_16x16x32_bf16 v[114:117], v[146:149], v[196:199], v[114:117]
	v_mfma_f32_16x16x32_bf16 v[106:109], v[162:165], v[196:199], v[106:109]
	v_mfma_f32_16x16x32_bf16 v[98:101], v[146:149], v[204:207], v[98:101]
	v_mfma_f32_16x16x32_bf16 v[90:93], v[162:165], v[204:207], v[90:93]
	v_mfma_f32_16x16x32_bf16 v[82:85], v[146:149], v[212:215], v[82:85]
	v_mfma_f32_16x16x32_bf16 v[74:77], v[162:165], v[212:215], v[74:77]
	s_setprio 0
	s_setprio 1
	v_mfma_f32_16x16x32_bf16 v[118:121], v[166:169], v[184:187], v[118:121]
	v_mfma_f32_16x16x32_bf16 v[110:113], v[174:177], v[184:187], v[110:113]
	v_mfma_f32_16x16x32_bf16 v[102:105], v[166:169], v[192:195], v[102:105]
	v_mfma_f32_16x16x32_bf16 v[94:97], v[174:177], v[192:195], v[94:97]
	v_mfma_f32_16x16x32_bf16 v[86:89], v[166:169], v[200:203], v[86:89]
	v_mfma_f32_16x16x32_bf16 v[78:81], v[174:177], v[200:203], v[78:81]
	v_mfma_f32_16x16x32_bf16 v[70:73], v[166:169], v[208:211], v[70:73]
	v_mfma_f32_16x16x32_bf16 v[66:69], v[174:177], v[208:211], v[66:69]
	v_mfma_f32_16x16x32_bf16 v[118:121], v[170:173], v[188:191], v[118:121]
	v_mfma_f32_16x16x32_bf16 v[110:113], v[180:183], v[188:191], v[110:113]
	v_mfma_f32_16x16x32_bf16 v[102:105], v[170:173], v[196:199], v[102:105]
	v_mfma_f32_16x16x32_bf16 v[94:97], v[180:183], v[196:199], v[94:97]
	v_mfma_f32_16x16x32_bf16 v[86:89], v[170:173], v[204:207], v[86:89]
	v_mfma_f32_16x16x32_bf16 v[78:81], v[180:183], v[204:207], v[78:81]
	v_mfma_f32_16x16x32_bf16 v[70:73], v[170:173], v[212:215], v[70:73]
	v_mfma_f32_16x16x32_bf16 v[66:69], v[180:183], v[212:215], v[66:69]
	s_barrier
	s_setprio 0
	s_add_i32 s58, s81, s61
	v_lshl_add_u64 v[134:135], v[134:135], 0, s[4:5]
	s_mov_b32 m0, s58
	ds_read_b128 v[184:187], v141 offset:49152
	ds_read_b128 v[188:191], v141 offset:50176
	ds_read_b128 v[192:195], v141 offset:51200
	ds_read_b128 v[196:199], v141 offset:52224
	ds_read_b128 v[200:203], v141 offset:53248
	ds_read_b128 v[204:207], v141 offset:54272
	ds_read_b128 v[208:211], v141 offset:55296
	ds_read_b128 v[212:215], v141 offset:56320
	global_load_lds_dwordx4 v[134:135], off
	s_add_i32 m0, s58, 0x2000
	s_add_u32 s56, s56, 0x80080
	v_lshl_add_u64 v[134:135], v[216:217], 0, s[4:5]
	s_addc_u32 s57, s57, 0
	s_add_i32 s58, s82, s61
	global_load_lds_dwordx4 v[134:135], off
	v_lshl_add_u64 v[134:135], s[56:57], 0, v[152:153]
	s_mov_b32 m0, s58
	s_nop 0
	global_load_lds_dwordx4 v[134:135], off
	v_lshl_add_u64 v[134:135], s[56:57], 0, v[156:157]
	s_add_i32 m0, s58, 0x2000
	s_nop 0
	global_load_lds_dwordx4 v[134:135], off
	v_lshl_add_u64 v[134:135], v[218:219], 0, s[4:5]
	s_mov_b32 m0, s66
	s_nop 0
	global_load_lds_dwordx4 v[134:135], off
	v_lshl_add_u64 v[134:135], v[220:221], 0, s[4:5]
	s_mov_b32 m0, s67
	s_nop 0
	global_load_lds_dwordx4 v[134:135], off
	s_waitcnt vmcnt(8)
	s_waitcnt lgkmcnt(0)
	s_setprio 1
	s_barrier
	v_mfma_f32_16x16x32_bf16 v[62:65], v[142:145], v[184:187], v[62:65]
	v_mfma_f32_16x16x32_bf16 v[58:61], v[158:161], v[184:187], v[58:61]
	v_mfma_f32_16x16x32_bf16 v[50:53], v[142:145], v[192:195], v[50:53]
	v_mfma_f32_16x16x32_bf16 v[42:45], v[158:161], v[192:195], v[42:45]
	v_mfma_f32_16x16x32_bf16 v[34:37], v[142:145], v[200:203], v[34:37]
	v_mfma_f32_16x16x32_bf16 v[26:29], v[158:161], v[200:203], v[26:29]
	v_mfma_f32_16x16x32_bf16 v[18:21], v[142:145], v[208:211], v[18:21]
	v_mfma_f32_16x16x32_bf16 v[10:13], v[158:161], v[208:211], v[10:13]
	v_mfma_f32_16x16x32_bf16 v[62:65], v[146:149], v[188:191], v[62:65]
	v_mfma_f32_16x16x32_bf16 v[58:61], v[162:165], v[188:191], v[58:61]
	v_mfma_f32_16x16x32_bf16 v[50:53], v[146:149], v[196:199], v[50:53]
	v_mfma_f32_16x16x32_bf16 v[42:45], v[162:165], v[196:199], v[42:45]
	v_mfma_f32_16x16x32_bf16 v[34:37], v[146:149], v[204:207], v[34:37]
	v_mfma_f32_16x16x32_bf16 v[26:29], v[162:165], v[204:207], v[26:29]
	v_mfma_f32_16x16x32_bf16 v[18:21], v[146:149], v[212:215], v[18:21]
	v_mfma_f32_16x16x32_bf16 v[10:13], v[162:165], v[212:215], v[10:13]
	s_setprio 0
	s_setprio 1
	v_mfma_f32_16x16x32_bf16 v[54:57], v[166:169], v[184:187], v[54:57]
	v_mfma_f32_16x16x32_bf16 v[46:49], v[174:177], v[184:187], v[46:49]
	v_mfma_f32_16x16x32_bf16 v[38:41], v[166:169], v[192:195], v[38:41]
	v_mfma_f32_16x16x32_bf16 v[30:33], v[174:177], v[192:195], v[30:33]
	v_mfma_f32_16x16x32_bf16 v[22:25], v[166:169], v[200:203], v[22:25]
	v_mfma_f32_16x16x32_bf16 v[14:17], v[174:177], v[200:203], v[14:17]
	v_mfma_f32_16x16x32_bf16 v[6:9], v[166:169], v[208:211], v[6:9]
	v_mfma_f32_16x16x32_bf16 v[2:5], v[174:177], v[208:211], v[2:5]
	v_mfma_f32_16x16x32_bf16 v[54:57], v[170:173], v[188:191], v[54:57]
	v_mfma_f32_16x16x32_bf16 v[46:49], v[180:183], v[188:191], v[46:49]
	v_mfma_f32_16x16x32_bf16 v[38:41], v[170:173], v[196:199], v[38:41]
	v_mfma_f32_16x16x32_bf16 v[30:33], v[180:183], v[196:199], v[30:33]
	v_mfma_f32_16x16x32_bf16 v[22:25], v[170:173], v[204:207], v[22:25]
	v_mfma_f32_16x16x32_bf16 v[14:17], v[180:183], v[204:207], v[14:17]
	v_mfma_f32_16x16x32_bf16 v[6:9], v[170:173], v[212:215], v[6:9]
	v_mfma_f32_16x16x32_bf16 v[2:5], v[180:183], v[212:215], v[2:5]
	s_barrier
	s_setprio 0
	s_add_i32 s80, s80, 2
	s_add_u32 s54, s54, 0x100
	s_addc_u32 s55, s55, 0
	s_add_u32 s78, s78, 0x100
	s_addc_u32 s79, s79, 0
	s_cmp_gt_u32 s80, 29

.LBB0_1407:
	s_ashr_i32 s39, s38, 31
	s_lshl_b64 s[40:41], s[38:39], 20
	s_add_u32 s40, s22, s40
	s_addc_u32 s41, s23, s41
	s_and_b64 s[42:43], s[10:11], exec
	s_cselect_b32 s39, s41, s47
	s_cselect_b32 s66, s40, s46
	s_ashr_i32 s37, s36, 31
	s_lshl_b64 s[42:43], s[36:37], 20
	s_add_u32 s42, s28, s42
	s_addc_u32 s43, s29, s43
	s_and_b64 s[52:53], s[10:11], exec
	s_cselect_b32 s37, s43, s49
	s_cselect_b32 s67, s42, s48
	s_add_u32 s46, s46, 0x80080
	s_addc_u32 s47, s47, 0
	s_add_u32 s68, s48, 0x100
	s_addc_u32 s69, s49, 0
	s_mov_b32 s70, -2
	ds_read_b128 v[130:133], v183
	ds_read_b128 v[134:137], v183 offset:1024
	ds_read_b128 v[138:141], v183 offset:2048
	ds_read_b128 v[142:145], v183 offset:3072
	ds_read_b128 v[162:165], v184
	ds_read_b128 v[166:169], v184 offset:1024
	ds_read_b128 v[170:173], v184 offset:2048
	ds_read_b128 v[174:177], v184 offset:3072
	s_add_u32 s48, s46, 0xfff80080
	s_addc_u32 s49, s47, -1
	s_cmp_eq_u32 s70, 28
	s_cselect_b32 s53, s39, s49
	s_cselect_b32 s52, s66, s48
	s_cselect_b32 s49, s37, s69
	s_cselect_b32 s48, s67, s68
	v_lshl_add_u64 v[178:179], s[46:47], 0, v[154:155]
	s_add_i32 m0, s45, 0xc000
	ds_read_b128 v[188:191], v185
	ds_read_b128 v[192:195], v185 offset:1024
	ds_read_b128 v[196:199], v185 offset:2048
	ds_read_b128 v[200:203], v185 offset:3072
	ds_read_b128 v[204:207], v185 offset:4096
	ds_read_b128 v[208:211], v185 offset:5120
	ds_read_b128 v[212:215], v185 offset:6144
	ds_read_b128 v[216:219], v185 offset:7168
	global_load_lds_dwordx4 v[178:179], off
	v_lshl_add_u64 v[178:179], s[46:47], 0, v[156:157]
	s_add_i32 m0, s45, 0xe000
	s_nop 0
	global_load_lds_dwordx4 v[178:179], off
	s_waitcnt vmcnt(8)
	s_waitcnt lgkmcnt(0)
	s_setprio 1
	s_barrier
	v_mfma_f32_16x16x32_bf16 v[126:129], v[130:133], v[188:191], 0
	v_mfma_f32_16x16x32_bf16 v[122:125], v[138:141], v[188:191], 0
	v_mfma_f32_16x16x32_bf16 v[110:113], v[130:133], v[196:199], 0
	v_mfma_f32_16x16x32_bf16 v[106:109], v[138:141], v[196:199], 0
	v_mfma_f32_16x16x32_bf16 v[94:97], v[130:133], v[204:207], 0
	v_mfma_f32_16x16x32_bf16 v[90:93], v[138:141], v[204:207], 0
	v_mfma_f32_16x16x32_bf16 v[78:81], v[130:133], v[212:215], 0
	v_mfma_f32_16x16x32_bf16 v[74:77], v[138:141], v[212:215], 0
	v_mfma_f32_16x16x32_bf16 v[126:129], v[134:137], v[192:195], v[126:129]
	v_mfma_f32_16x16x32_bf16 v[122:125], v[142:145], v[192:195], v[122:125]
	v_mfma_f32_16x16x32_bf16 v[110:113], v[134:137], v[200:203], v[110:113]
	v_mfma_f32_16x16x32_bf16 v[106:109], v[142:145], v[200:203], v[106:109]
	v_mfma_f32_16x16x32_bf16 v[94:97], v[134:137], v[208:211], v[94:97]
	v_mfma_f32_16x16x32_bf16 v[90:93], v[142:145], v[208:211], v[90:93]
	v_mfma_f32_16x16x32_bf16 v[78:81], v[134:137], v[216:219], v[78:81]
	v_mfma_f32_16x16x32_bf16 v[74:77], v[142:145], v[216:219], v[74:77]
	s_setprio 0
	s_setprio 1
	v_mfma_f32_16x16x32_bf16 v[118:121], v[162:165], v[188:191], 0
	v_mfma_f32_16x16x32_bf16 v[114:117], v[170:173], v[188:191], 0
	v_mfma_f32_16x16x32_bf16 v[102:105], v[162:165], v[196:199], 0
	v_mfma_f32_16x16x32_bf16 v[98:101], v[170:173], v[196:199], 0
	v_mfma_f32_16x16x32_bf16 v[86:89], v[162:165], v[204:207], 0
	v_mfma_f32_16x16x32_bf16 v[82:85], v[170:173], v[204:207], 0
	v_mfma_f32_16x16x32_bf16 v[70:73], v[162:165], v[212:215], 0
	v_mfma_f32_16x16x32_bf16 v[66:69], v[170:173], v[212:215], 0
	v_mfma_f32_16x16x32_bf16 v[118:121], v[166:169], v[192:195], v[118:121]
	v_mfma_f32_16x16x32_bf16 v[114:117], v[174:177], v[192:195], v[114:117]
	v_mfma_f32_16x16x32_bf16 v[102:105], v[166:169], v[200:203], v[102:105]
	v_mfma_f32_16x16x32_bf16 v[98:101], v[174:177], v[200:203], v[98:101]
	v_mfma_f32_16x16x32_bf16 v[86:89], v[166:169], v[208:211], v[86:89]
	v_mfma_f32_16x16x32_bf16 v[82:85], v[174:177], v[208:211], v[82:85]
	v_mfma_f32_16x16x32_bf16 v[70:73], v[166:169], v[216:219], v[70:73]
	v_mfma_f32_16x16x32_bf16 v[66:69], v[174:177], v[216:219], v[66:69]
	s_barrier
	s_setprio 0
	s_add_i32 s71, s63, s54
	v_lshl_add_u64 v[178:179], s[48:49], 0, v[148:149]
	s_mov_b32 m0, s71
	ds_read_b128 v[188:191], v185 offset:16384
	ds_read_b128 v[192:195], v185 offset:17408
	ds_read_b128 v[196:199], v185 offset:18432
	ds_read_b128 v[200:203], v185 offset:19456
	ds_read_b128 v[204:207], v185 offset:20480
	ds_read_b128 v[208:211], v185 offset:21504
	ds_read_b128 v[212:215], v185 offset:22528
	ds_read_b128 v[216:219], v185 offset:23552
	global_load_lds_dwordx4 v[178:179], off
	s_add_i32 m0, s71, 0x2000
	s_add_u32 s72, s48, 0x80000
	v_lshl_add_u64 v[220:221], s[48:49], 0, v[152:153]
	s_addc_u32 s73, s49, 0
	s_add_i32 s71, s64, s54
	global_load_lds_dwordx4 v[220:221], off
	v_lshl_add_u64 v[222:223], s[72:73], 0, v[148:149]
	s_mov_b32 m0, s71
	v_lshl_add_u64 v[224:225], s[52:53], 0, v[150:151]
	global_load_lds_dwordx4 v[222:223], off
	v_lshl_add_u64 v[222:223], s[72:73], 0, v[152:153]
	s_add_i32 m0, s71, 0x2000
	s_nop 0
	global_load_lds_dwordx4 v[222:223], off
	v_lshl_add_u64 v[222:223], s[52:53], 0, v[146:147]
	s_mov_b32 m0, s45
	s_nop 0
	global_load_lds_dwordx4 v[222:223], off
	s_mov_b32 m0, s55
	s_nop 0
	global_load_lds_dwordx4 v[224:225], off
	s_waitcnt vmcnt(8)
	s_waitcnt lgkmcnt(0)
	s_setprio 1
	s_barrier
	v_mfma_f32_16x16x32_bf16 v[62:65], v[130:133], v[188:191], 0
	v_mfma_f32_16x16x32_bf16 v[58:61], v[138:141], v[188:191], 0
	v_mfma_f32_16x16x32_bf16 v[46:49], v[130:133], v[196:199], 0
	v_mfma_f32_16x16x32_bf16 v[42:45], v[138:141], v[196:199], 0
	v_mfma_f32_16x16x32_bf16 v[30:33], v[130:133], v[204:207], 0
	v_mfma_f32_16x16x32_bf16 v[26:29], v[138:141], v[204:207], 0
	v_mfma_f32_16x16x32_bf16 v[14:17], v[130:133], v[212:215], 0
	v_mfma_f32_16x16x32_bf16 v[10:13], v[138:141], v[212:215], 0
	v_mfma_f32_16x16x32_bf16 v[62:65], v[134:137], v[192:195], v[62:65]
	v_mfma_f32_16x16x32_bf16 v[58:61], v[142:145], v[192:195], v[58:61]
	v_mfma_f32_16x16x32_bf16 v[46:49], v[134:137], v[200:203], v[46:49]
	v_mfma_f32_16x16x32_bf16 v[42:45], v[142:145], v[200:203], v[42:45]
	v_mfma_f32_16x16x32_bf16 v[30:33], v[134:137], v[208:211], v[30:33]
	v_mfma_f32_16x16x32_bf16 v[26:29], v[142:145], v[208:211], v[26:29]
	v_mfma_f32_16x16x32_bf16 v[14:17], v[134:137], v[216:219], v[14:17]
	v_mfma_f32_16x16x32_bf16 v[10:13], v[142:145], v[216:219], v[10:13]
	s_setprio 0
	s_setprio 1
	v_mfma_f32_16x16x32_bf16 v[54:57], v[162:165], v[188:191], 0
	v_mfma_f32_16x16x32_bf16 v[50:53], v[170:173], v[188:191], 0
	v_mfma_f32_16x16x32_bf16 v[38:41], v[162:165], v[196:199], 0
	v_mfma_f32_16x16x32_bf16 v[34:37], v[170:173], v[196:199], 0
	v_mfma_f32_16x16x32_bf16 v[22:25], v[162:165], v[204:207], 0
	v_mfma_f32_16x16x32_bf16 v[18:21], v[170:173], v[204:207], 0
	v_mfma_f32_16x16x32_bf16 v[6:9], v[162:165], v[212:215], 0
	v_mfma_f32_16x16x32_bf16 v[2:5], v[170:173], v[212:215], 0
	v_mfma_f32_16x16x32_bf16 v[54:57], v[166:169], v[192:195], v[54:57]
	v_mfma_f32_16x16x32_bf16 v[50:53], v[174:177], v[192:195], v[50:53]
	v_mfma_f32_16x16x32_bf16 v[38:41], v[166:169], v[200:203], v[38:41]
	v_mfma_f32_16x16x32_bf16 v[34:37], v[174:177], v[200:203], v[34:37]
	v_mfma_f32_16x16x32_bf16 v[22:25], v[166:169], v[208:211], v[22:25]
	v_mfma_f32_16x16x32_bf16 v[18:21], v[174:177], v[208:211], v[18:21]
	v_mfma_f32_16x16x32_bf16 v[6:9], v[166:169], v[216:219], v[6:9]
	v_mfma_f32_16x16x32_bf16 v[2:5], v[174:177], v[216:219], v[2:5]
	s_barrier
	s_setprio 0
	s_add_i32 s71, 0, 0x18000
	v_add_u32_e32 v1, s71, v181
	s_add_i32 s72, 0, 0x1c000
	ds_read_b128 v[130:133], v1
	ds_read_b128 v[134:137], v1 offset:1024
	ds_read_b128 v[138:141], v1 offset:2048
	ds_read_b128 v[142:145], v1 offset:3072
	v_add_u32_e32 v1, s72, v181
	ds_read_b128 v[162:165], v1
	ds_read_b128 v[166:169], v1 offset:1024
	ds_read_b128 v[170:173], v1 offset:2048
	ds_read_b128 v[174:177], v1 offset:3072
	s_add_u32 s52, s52, 0x80000
	s_addc_u32 s53, s53, 0
	s_mov_b32 m0, s56
	v_lshl_add_u64 v[226:227], s[52:53], 0, v[146:147]
	ds_read_b128 v[188:191], v185 offset:32768
	ds_read_b128 v[192:195], v185 offset:33792
	ds_read_b128 v[196:199], v185 offset:34816
	ds_read_b128 v[200:203], v185 offset:35840
	ds_read_b128 v[204:207], v185 offset:36864
	ds_read_b128 v[208:211], v185 offset:37888
	ds_read_b128 v[212:215], v185 offset:38912
	ds_read_b128 v[216:219], v185 offset:39936
	global_load_lds_dwordx4 v[226:227], off
	v_lshl_add_u64 v[226:227], s[52:53], 0, v[150:151]
	s_mov_b32 m0, s57
	s_nop 0
	global_load_lds_dwordx4 v[226:227], off
	s_waitcnt vmcnt(8)
	s_waitcnt lgkmcnt(0)
	s_setprio 1
	s_barrier
	v_mfma_f32_16x16x32_bf16 v[126:129], v[130:133], v[188:191], v[126:129]
	v_mfma_f32_16x16x32_bf16 v[122:125], v[138:141], v[188:191], v[122:125]
	v_mfma_f32_16x16x32_bf16 v[110:113], v[130:133], v[196:199], v[110:113]
	v_mfma_f32_16x16x32_bf16 v[106:109], v[138:141], v[196:199], v[106:109]
	v_mfma_f32_16x16x32_bf16 v[94:97], v[130:133], v[204:207], v[94:97]
	v_mfma_f32_16x16x32_bf16 v[90:93], v[138:141], v[204:207], v[90:93]
	v_mfma_f32_16x16x32_bf16 v[78:81], v[130:133], v[212:215], v[78:81]
	v_mfma_f32_16x16x32_bf16 v[74:77], v[138:141], v[212:215], v[74:77]
	v_mfma_f32_16x16x32_bf16 v[126:129], v[134:137], v[192:195], v[126:129]
	v_mfma_f32_16x16x32_bf16 v[122:125], v[142:145], v[192:195], v[122:125]
	v_mfma_f32_16x16x32_bf16 v[110:113], v[134:137], v[200:203], v[110:113]
	v_mfma_f32_16x16x32_bf16 v[106:109], v[142:145], v[200:203], v[106:109]
	v_mfma_f32_16x16x32_bf16 v[94:97], v[134:137], v[208:211], v[94:97]
	v_mfma_f32_16x16x32_bf16 v[90:93], v[142:145], v[208:211], v[90:93]
	v_mfma_f32_16x16x32_bf16 v[78:81], v[134:137], v[216:219], v[78:81]
	v_mfma_f32_16x16x32_bf16 v[74:77], v[142:145], v[216:219], v[74:77]
	s_setprio 0
	s_setprio 1
	v_mfma_f32_16x16x32_bf16 v[118:121], v[162:165], v[188:191], v[118:121]
	v_mfma_f32_16x16x32_bf16 v[114:117], v[170:173], v[188:191], v[114:117]
	v_mfma_f32_16x16x32_bf16 v[102:105], v[162:165], v[196:199], v[102:105]
	v_mfma_f32_16x16x32_bf16 v[98:101], v[170:173], v[196:199], v[98:101]
	v_mfma_f32_16x16x32_bf16 v[86:89], v[162:165], v[204:207], v[86:89]
	v_mfma_f32_16x16x32_bf16 v[82:85], v[170:173], v[204:207], v[82:85]
	v_mfma_f32_16x16x32_bf16 v[70:73], v[162:165], v[212:215], v[70:73]
	v_mfma_f32_16x16x32_bf16 v[66:69], v[170:173], v[212:215], v[66:69]
	v_mfma_f32_16x16x32_bf16 v[118:121], v[166:169], v[192:195], v[118:121]
	v_mfma_f32_16x16x32_bf16 v[114:117], v[174:177], v[192:195], v[114:117]
	v_mfma_f32_16x16x32_bf16 v[102:105], v[166:169], v[200:203], v[102:105]
	v_mfma_f32_16x16x32_bf16 v[98:101], v[174:177], v[200:203], v[98:101]
	v_mfma_f32_16x16x32_bf16 v[86:89], v[166:169], v[208:211], v[86:89]
	v_mfma_f32_16x16x32_bf16 v[82:85], v[174:177], v[208:211], v[82:85]
	v_mfma_f32_16x16x32_bf16 v[70:73], v[166:169], v[216:219], v[70:73]
	v_mfma_f32_16x16x32_bf16 v[66:69], v[174:177], v[216:219], v[66:69]
	s_barrier
	s_setprio 0
	s_add_i32 s52, s71, s54
	v_lshl_add_u64 v[178:179], v[178:179], 0, s[30:31]
	s_mov_b32 m0, s52
	ds_read_b128 v[188:191], v185 offset:49152
	ds_read_b128 v[192:195], v185 offset:50176
	ds_read_b128 v[196:199], v185 offset:51200
	ds_read_b128 v[200:203], v185 offset:52224
	ds_read_b128 v[204:207], v185 offset:53248
	ds_read_b128 v[208:211], v185 offset:54272
	ds_read_b128 v[212:215], v185 offset:55296
	ds_read_b128 v[216:219], v185 offset:56320
	global_load_lds_dwordx4 v[178:179], off
	s_add_i32 m0, s52, 0x2000
	s_add_u32 s48, s48, 0x80080
	v_lshl_add_u64 v[178:179], v[220:221], 0, s[30:31]
	s_addc_u32 s49, s49, 0
	s_add_i32 s52, s72, s54
	global_load_lds_dwordx4 v[178:179], off
	v_lshl_add_u64 v[178:179], s[48:49], 0, v[148:149]
	s_mov_b32 m0, s52
	s_nop 0
	global_load_lds_dwordx4 v[178:179], off
	v_lshl_add_u64 v[178:179], s[48:49], 0, v[152:153]
	s_add_i32 m0, s52, 0x2000
	s_nop 0
	global_load_lds_dwordx4 v[178:179], off
	v_lshl_add_u64 v[178:179], v[222:223], 0, s[30:31]
	s_mov_b32 m0, s60
	s_nop 0
	global_load_lds_dwordx4 v[178:179], off
	v_lshl_add_u64 v[178:179], v[224:225], 0, s[30:31]
	s_mov_b32 m0, s61
	s_nop 0
	global_load_lds_dwordx4 v[178:179], off
	s_waitcnt vmcnt(8)
	s_waitcnt lgkmcnt(0)
	s_setprio 1
	s_barrier
	v_mfma_f32_16x16x32_bf16 v[62:65], v[130:133], v[188:191], v[62:65]
	v_mfma_f32_16x16x32_bf16 v[58:61], v[138:141], v[188:191], v[58:61]
	v_mfma_f32_16x16x32_bf16 v[46:49], v[130:133], v[196:199], v[46:49]
	v_mfma_f32_16x16x32_bf16 v[42:45], v[138:141], v[196:199], v[42:45]
	v_mfma_f32_16x16x32_bf16 v[30:33], v[130:133], v[204:207], v[30:33]
	v_mfma_f32_16x16x32_bf16 v[26:29], v[138:141], v[204:207], v[26:29]
	v_mfma_f32_16x16x32_bf16 v[14:17], v[130:133], v[212:215], v[14:17]
	v_mfma_f32_16x16x32_bf16 v[10:13], v[138:141], v[212:215], v[10:13]
	v_mfma_f32_16x16x32_bf16 v[62:65], v[134:137], v[192:195], v[62:65]
	v_mfma_f32_16x16x32_bf16 v[58:61], v[142:145], v[192:195], v[58:61]
	v_mfma_f32_16x16x32_bf16 v[46:49], v[134:137], v[200:203], v[46:49]
	v_mfma_f32_16x16x32_bf16 v[42:45], v[142:145], v[200:203], v[42:45]
	v_mfma_f32_16x16x32_bf16 v[30:33], v[134:137], v[208:211], v[30:33]
	v_mfma_f32_16x16x32_bf16 v[26:29], v[142:145], v[208:211], v[26:29]
	v_mfma_f32_16x16x32_bf16 v[14:17], v[134:137], v[216:219], v[14:17]
	v_mfma_f32_16x16x32_bf16 v[10:13], v[142:145], v[216:219], v[10:13]
	s_setprio 0
	s_setprio 1
	v_mfma_f32_16x16x32_bf16 v[54:57], v[162:165], v[188:191], v[54:57]
	v_mfma_f32_16x16x32_bf16 v[50:53], v[170:173], v[188:191], v[50:53]
	v_mfma_f32_16x16x32_bf16 v[38:41], v[162:165], v[196:199], v[38:41]
	v_mfma_f32_16x16x32_bf16 v[34:37], v[170:173], v[196:199], v[34:37]
	v_mfma_f32_16x16x32_bf16 v[22:25], v[162:165], v[204:207], v[22:25]
	v_mfma_f32_16x16x32_bf16 v[18:21], v[170:173], v[204:207], v[18:21]
	v_mfma_f32_16x16x32_bf16 v[6:9], v[162:165], v[212:215], v[6:9]
	v_mfma_f32_16x16x32_bf16 v[2:5], v[170:173], v[212:215], v[2:5]
	v_mfma_f32_16x16x32_bf16 v[54:57], v[166:169], v[192:195], v[54:57]
	v_mfma_f32_16x16x32_bf16 v[50:53], v[174:177], v[192:195], v[50:53]
	v_mfma_f32_16x16x32_bf16 v[38:41], v[166:169], v[200:203], v[38:41]
	v_mfma_f32_16x16x32_bf16 v[34:37], v[174:177], v[200:203], v[34:37]
	v_mfma_f32_16x16x32_bf16 v[22:25], v[166:169], v[208:211], v[22:25]
	v_mfma_f32_16x16x32_bf16 v[18:21], v[174:177], v[208:211], v[18:21]
	v_mfma_f32_16x16x32_bf16 v[6:9], v[166:169], v[216:219], v[6:9]
	v_mfma_f32_16x16x32_bf16 v[2:5], v[174:177], v[216:219], v[2:5]
	s_barrier
	s_setprio 0
	s_add_i32 s70, s70, 2
	s_add_u32 s46, s46, 0x100
	s_addc_u32 s47, s47, 0
	s_add_u32 s68, s68, 0x100
	s_addc_u32 s69, s69, 0
	s_cmp_gt_u32 s70, 29

.LBB0_1478:
	s_ashr_i32 s11, s10, 31
	s_lshl_b64 s[6:7], s[10:11], 20
	s_add_u32 s38, s19, s6
	s_addc_u32 s39, s22, s7
	s_and_b64 s[6:7], s[2:3], exec
	s_cselect_b32 s9, s39, s1
	s_cselect_b32 s11, s38, s0
	s_ashr_i32 s37, s36, 31
	s_lshl_b64 s[6:7], s[36:37], 20
	s_add_u32 s40, s23, s6
	s_addc_u32 s41, s28, s7
	s_and_b64 s[6:7], s[2:3], exec
	s_cselect_b32 s37, s41, s5
	s_cselect_b32 s60, s40, s4
	s_add_u32 s0, s0, 0x80080
	s_addc_u32 s1, s1, 0
	s_add_u32 s61, s4, 0x100
	s_addc_u32 s62, s5, 0
	s_mov_b32 s63, -2
	ds_read_b128 v[132:135], v174
	ds_read_b128 v[158:161], v174 offset:1024
	ds_read_b128 v[166:169], v174 offset:2048
	ds_read_b128 v[170:173], v174 offset:3072
	ds_read_b128 v[182:185], v175
	ds_read_b128 v[186:189], v175 offset:1024
	ds_read_b128 v[190:193], v175 offset:2048
	ds_read_b128 v[194:197], v175 offset:3072
	s_add_u32 s4, s0, 0xfff80080
	s_addc_u32 s5, s1, -1
	s_cmp_eq_u32 s63, 28
	s_cselect_b32 s7, s9, s5
	s_cselect_b32 s6, s11, s4
	s_cselect_b32 s5, s37, s62
	s_cselect_b32 s4, s60, s61
	v_lshl_add_u64 v[136:137], s[0:1], 0, v[146:147]
	s_add_i32 m0, s44, 0xc000
	ds_read_b128 v[198:201], v176
	ds_read_b128 v[202:205], v176 offset:1024
	ds_read_b128 v[206:209], v176 offset:2048
	ds_read_b128 v[210:213], v176 offset:3072
	ds_read_b128 v[214:217], v176 offset:4096
	ds_read_b128 v[218:221], v176 offset:5120
	ds_read_b128 v[222:225], v176 offset:6144
	ds_read_b128 v[226:229], v176 offset:7168
	global_load_lds_dwordx4 v[136:137], off
	v_lshl_add_u64 v[136:137], s[0:1], 0, v[148:149]
	s_add_i32 m0, s44, 0xe000
	s_nop 0
	global_load_lds_dwordx4 v[136:137], off
	s_waitcnt vmcnt(8)
	s_waitcnt lgkmcnt(0)
	s_setprio 1
	s_barrier
	v_mfma_f32_16x16x32_bf16 v[128:131], v[132:135], v[198:201], 0
	v_mfma_f32_16x16x32_bf16 v[124:127], v[166:169], v[198:201], 0
	v_mfma_f32_16x16x32_bf16 v[112:115], v[132:135], v[206:209], 0
	v_mfma_f32_16x16x32_bf16 v[108:111], v[166:169], v[206:209], 0
	v_mfma_f32_16x16x32_bf16 v[96:99], v[132:135], v[214:217], 0
	v_mfma_f32_16x16x32_bf16 v[92:95], v[166:169], v[214:217], 0
	v_mfma_f32_16x16x32_bf16 v[80:83], v[132:135], v[222:225], 0
	v_mfma_f32_16x16x32_bf16 v[76:79], v[166:169], v[222:225], 0
	v_mfma_f32_16x16x32_bf16 v[128:131], v[158:161], v[202:205], v[128:131]
	v_mfma_f32_16x16x32_bf16 v[124:127], v[170:173], v[202:205], v[124:127]
	v_mfma_f32_16x16x32_bf16 v[112:115], v[158:161], v[210:213], v[112:115]
	v_mfma_f32_16x16x32_bf16 v[108:111], v[170:173], v[210:213], v[108:111]
	v_mfma_f32_16x16x32_bf16 v[96:99], v[158:161], v[218:221], v[96:99]
	v_mfma_f32_16x16x32_bf16 v[92:95], v[170:173], v[218:221], v[92:95]
	v_mfma_f32_16x16x32_bf16 v[80:83], v[158:161], v[226:229], v[80:83]
	v_mfma_f32_16x16x32_bf16 v[76:79], v[170:173], v[226:229], v[76:79]
	s_setprio 0
	s_setprio 1
	v_mfma_f32_16x16x32_bf16 v[120:123], v[182:185], v[198:201], 0
	v_mfma_f32_16x16x32_bf16 v[116:119], v[190:193], v[198:201], 0
	v_mfma_f32_16x16x32_bf16 v[104:107], v[182:185], v[206:209], 0
	v_mfma_f32_16x16x32_bf16 v[100:103], v[190:193], v[206:209], 0
	v_mfma_f32_16x16x32_bf16 v[88:91], v[182:185], v[214:217], 0
	v_mfma_f32_16x16x32_bf16 v[84:87], v[190:193], v[214:217], 0
	v_mfma_f32_16x16x32_bf16 v[72:75], v[182:185], v[222:225], 0
	v_mfma_f32_16x16x32_bf16 v[68:71], v[190:193], v[222:225], 0
	v_mfma_f32_16x16x32_bf16 v[120:123], v[186:189], v[202:205], v[120:123]
	v_mfma_f32_16x16x32_bf16 v[116:119], v[194:197], v[202:205], v[116:119]
	v_mfma_f32_16x16x32_bf16 v[104:107], v[186:189], v[210:213], v[104:107]
	v_mfma_f32_16x16x32_bf16 v[100:103], v[194:197], v[210:213], v[100:103]
	v_mfma_f32_16x16x32_bf16 v[88:91], v[186:189], v[218:221], v[88:91]
	v_mfma_f32_16x16x32_bf16 v[84:87], v[194:197], v[218:221], v[84:87]
	v_mfma_f32_16x16x32_bf16 v[72:75], v[186:189], v[226:229], v[72:75]
	v_mfma_f32_16x16x32_bf16 v[68:71], v[194:197], v[226:229], v[68:71]
	s_barrier
	s_setprio 0
	s_add_i32 s64, s54, s29
	v_lshl_add_u64 v[136:137], s[4:5], 0, v[142:143]
	s_mov_b32 m0, s64
	ds_read_b128 v[198:201], v176 offset:16384
	ds_read_b128 v[202:205], v176 offset:17408
	ds_read_b128 v[206:209], v176 offset:18432
	ds_read_b128 v[210:213], v176 offset:19456
	ds_read_b128 v[214:217], v176 offset:20480
	ds_read_b128 v[218:221], v176 offset:21504
	ds_read_b128 v[222:225], v176 offset:22528
	ds_read_b128 v[226:229], v176 offset:23552
	global_load_lds_dwordx4 v[136:137], off
	s_add_i32 m0, s64, 0x2000
	s_add_u32 s64, s4, 0x80000
	v_lshl_add_u64 v[230:231], s[4:5], 0, v[138:139]
	s_addc_u32 s65, s5, 0
	s_add_i32 s66, s55, s29
	global_load_lds_dwordx4 v[230:231], off
	v_lshl_add_u64 v[232:233], s[64:65], 0, v[142:143]
	s_mov_b32 m0, s66
	v_lshl_add_u64 v[234:235], s[6:7], 0, v[140:141]
	global_load_lds_dwordx4 v[232:233], off
	v_lshl_add_u64 v[232:233], s[64:65], 0, v[138:139]
	s_add_i32 m0, s66, 0x2000
	s_nop 0
	global_load_lds_dwordx4 v[232:233], off
	v_lshl_add_u64 v[232:233], s[6:7], 0, v[144:145]
	s_mov_b32 m0, s44
	s_nop 0
	global_load_lds_dwordx4 v[232:233], off
	s_mov_b32 m0, s45
	s_nop 0
	global_load_lds_dwordx4 v[234:235], off
	s_waitcnt vmcnt(8)
	s_waitcnt lgkmcnt(0)
	s_setprio 1
	s_barrier
	v_mfma_f32_16x16x32_bf16 v[62:65], v[132:135], v[198:201], 0
	v_mfma_f32_16x16x32_bf16 v[58:61], v[166:169], v[198:201], 0
	v_mfma_f32_16x16x32_bf16 v[46:49], v[132:135], v[206:209], 0
	v_mfma_f32_16x16x32_bf16 v[42:45], v[166:169], v[206:209], 0
	v_mfma_f32_16x16x32_bf16 v[30:33], v[132:135], v[214:217], 0
	v_mfma_f32_16x16x32_bf16 v[26:29], v[166:169], v[214:217], 0
	v_mfma_f32_16x16x32_bf16 v[14:17], v[132:135], v[222:225], 0
	v_mfma_f32_16x16x32_bf16 v[10:13], v[166:169], v[222:225], 0
	v_mfma_f32_16x16x32_bf16 v[62:65], v[158:161], v[202:205], v[62:65]
	v_mfma_f32_16x16x32_bf16 v[58:61], v[170:173], v[202:205], v[58:61]
	v_mfma_f32_16x16x32_bf16 v[46:49], v[158:161], v[210:213], v[46:49]
	v_mfma_f32_16x16x32_bf16 v[42:45], v[170:173], v[210:213], v[42:45]
	v_mfma_f32_16x16x32_bf16 v[30:33], v[158:161], v[218:221], v[30:33]
	v_mfma_f32_16x16x32_bf16 v[26:29], v[170:173], v[218:221], v[26:29]
	v_mfma_f32_16x16x32_bf16 v[14:17], v[158:161], v[226:229], v[14:17]
	v_mfma_f32_16x16x32_bf16 v[10:13], v[170:173], v[226:229], v[10:13]
	s_setprio 0
	s_setprio 1
	v_mfma_f32_16x16x32_bf16 v[54:57], v[182:185], v[198:201], 0
	v_mfma_f32_16x16x32_bf16 v[50:53], v[190:193], v[198:201], 0
	v_mfma_f32_16x16x32_bf16 v[38:41], v[182:185], v[206:209], 0
	v_mfma_f32_16x16x32_bf16 v[34:37], v[190:193], v[206:209], 0
	v_mfma_f32_16x16x32_bf16 v[22:25], v[182:185], v[214:217], 0
	v_mfma_f32_16x16x32_bf16 v[18:21], v[190:193], v[214:217], 0
	v_mfma_f32_16x16x32_bf16 v[6:9], v[182:185], v[222:225], 0
	v_mfma_f32_16x16x32_bf16 v[2:5], v[190:193], v[222:225], 0
	v_mfma_f32_16x16x32_bf16 v[54:57], v[186:189], v[202:205], v[54:57]
	v_mfma_f32_16x16x32_bf16 v[50:53], v[194:197], v[202:205], v[50:53]
	v_mfma_f32_16x16x32_bf16 v[38:41], v[186:189], v[210:213], v[38:41]
	v_mfma_f32_16x16x32_bf16 v[34:37], v[194:197], v[210:213], v[34:37]
	v_mfma_f32_16x16x32_bf16 v[22:25], v[186:189], v[218:221], v[22:25]
	v_mfma_f32_16x16x32_bf16 v[18:21], v[194:197], v[218:221], v[18:21]
	v_mfma_f32_16x16x32_bf16 v[6:9], v[186:189], v[226:229], v[6:9]
	v_mfma_f32_16x16x32_bf16 v[2:5], v[194:197], v[226:229], v[2:5]
	s_barrier
	s_setprio 0
	s_add_i32 s64, 0, 0x18000
	v_add_u32_e32 v162, s64, v163
	s_add_i32 s65, 0, 0x1c000
	ds_read_b128 v[132:135], v162
	ds_read_b128 v[158:161], v162 offset:1024
	ds_read_b128 v[166:169], v162 offset:2048
	ds_read_b128 v[170:173], v162 offset:3072
	v_add_u32_e32 v162, s65, v163
	ds_read_b128 v[182:185], v162
	ds_read_b128 v[186:189], v162 offset:1024
	ds_read_b128 v[190:193], v162 offset:2048
	ds_read_b128 v[194:197], v162 offset:3072
	s_add_u32 s6, s6, 0x80000
	s_addc_u32 s7, s7, 0
	s_mov_b32 m0, s46
	v_lshl_add_u64 v[236:237], s[6:7], 0, v[144:145]
	ds_read_b128 v[198:201], v176 offset:32768
	ds_read_b128 v[202:205], v176 offset:33792
	ds_read_b128 v[206:209], v176 offset:34816
	ds_read_b128 v[210:213], v176 offset:35840
	ds_read_b128 v[214:217], v176 offset:36864
	ds_read_b128 v[218:221], v176 offset:37888
	ds_read_b128 v[222:225], v176 offset:38912
	ds_read_b128 v[226:229], v176 offset:39936
	global_load_lds_dwordx4 v[236:237], off
	v_lshl_add_u64 v[236:237], s[6:7], 0, v[140:141]
	s_mov_b32 m0, s47
	s_nop 0
	global_load_lds_dwordx4 v[236:237], off
	s_waitcnt vmcnt(8)
	s_waitcnt lgkmcnt(0)
	s_setprio 1
	s_barrier
	v_mfma_f32_16x16x32_bf16 v[128:131], v[132:135], v[198:201], v[128:131]
	v_mfma_f32_16x16x32_bf16 v[124:127], v[166:169], v[198:201], v[124:127]
	v_mfma_f32_16x16x32_bf16 v[112:115], v[132:135], v[206:209], v[112:115]
	v_mfma_f32_16x16x32_bf16 v[108:111], v[166:169], v[206:209], v[108:111]
	v_mfma_f32_16x16x32_bf16 v[96:99], v[132:135], v[214:217], v[96:99]
	v_mfma_f32_16x16x32_bf16 v[92:95], v[166:169], v[214:217], v[92:95]
	v_mfma_f32_16x16x32_bf16 v[80:83], v[132:135], v[222:225], v[80:83]
	v_mfma_f32_16x16x32_bf16 v[76:79], v[166:169], v[222:225], v[76:79]
	v_mfma_f32_16x16x32_bf16 v[128:131], v[158:161], v[202:205], v[128:131]
	v_mfma_f32_16x16x32_bf16 v[124:127], v[170:173], v[202:205], v[124:127]
	v_mfma_f32_16x16x32_bf16 v[112:115], v[158:161], v[210:213], v[112:115]
	v_mfma_f32_16x16x32_bf16 v[108:111], v[170:173], v[210:213], v[108:111]
	v_mfma_f32_16x16x32_bf16 v[96:99], v[158:161], v[218:221], v[96:99]
	v_mfma_f32_16x16x32_bf16 v[92:95], v[170:173], v[218:221], v[92:95]
	v_mfma_f32_16x16x32_bf16 v[80:83], v[158:161], v[226:229], v[80:83]
	v_mfma_f32_16x16x32_bf16 v[76:79], v[170:173], v[226:229], v[76:79]
	s_setprio 0
	s_setprio 1
	v_mfma_f32_16x16x32_bf16 v[120:123], v[182:185], v[198:201], v[120:123]
	v_mfma_f32_16x16x32_bf16 v[116:119], v[190:193], v[198:201], v[116:119]
	v_mfma_f32_16x16x32_bf16 v[104:107], v[182:185], v[206:209], v[104:107]
	v_mfma_f32_16x16x32_bf16 v[100:103], v[190:193], v[206:209], v[100:103]
	v_mfma_f32_16x16x32_bf16 v[88:91], v[182:185], v[214:217], v[88:91]
	v_mfma_f32_16x16x32_bf16 v[84:87], v[190:193], v[214:217], v[84:87]
	v_mfma_f32_16x16x32_bf16 v[72:75], v[182:185], v[222:225], v[72:75]
	v_mfma_f32_16x16x32_bf16 v[68:71], v[190:193], v[222:225], v[68:71]
	v_mfma_f32_16x16x32_bf16 v[120:123], v[186:189], v[202:205], v[120:123]
	v_mfma_f32_16x16x32_bf16 v[116:119], v[194:197], v[202:205], v[116:119]
	v_mfma_f32_16x16x32_bf16 v[104:107], v[186:189], v[210:213], v[104:107]
	v_mfma_f32_16x16x32_bf16 v[100:103], v[194:197], v[210:213], v[100:103]
	v_mfma_f32_16x16x32_bf16 v[88:91], v[186:189], v[218:221], v[88:91]
	v_mfma_f32_16x16x32_bf16 v[84:87], v[194:197], v[218:221], v[84:87]
	v_mfma_f32_16x16x32_bf16 v[72:75], v[186:189], v[226:229], v[72:75]
	v_mfma_f32_16x16x32_bf16 v[68:71], v[194:197], v[226:229], v[68:71]
	s_barrier
	s_setprio 0
	s_add_i32 s6, s64, s29
	v_lshl_add_u64 v[136:137], v[136:137], 0, s[30:31]
	s_mov_b32 m0, s6
	ds_read_b128 v[198:201], v176 offset:49152
	ds_read_b128 v[202:205], v176 offset:50176
	ds_read_b128 v[206:209], v176 offset:51200
	ds_read_b128 v[210:213], v176 offset:52224
	ds_read_b128 v[214:217], v176 offset:53248
	ds_read_b128 v[218:221], v176 offset:54272
	ds_read_b128 v[222:225], v176 offset:55296
	ds_read_b128 v[226:229], v176 offset:56320
	global_load_lds_dwordx4 v[136:137], off
	s_add_i32 m0, s6, 0x2000
	s_add_u32 s4, s4, 0x80080
	v_lshl_add_u64 v[136:137], v[230:231], 0, s[30:31]
	s_addc_u32 s5, s5, 0
	s_add_i32 s6, s65, s29
	global_load_lds_dwordx4 v[136:137], off
	v_lshl_add_u64 v[136:137], s[4:5], 0, v[142:143]
	s_mov_b32 m0, s6
	s_nop 0
	global_load_lds_dwordx4 v[136:137], off
	v_lshl_add_u64 v[136:137], s[4:5], 0, v[138:139]
	s_add_i32 m0, s6, 0x2000
	s_nop 0
	global_load_lds_dwordx4 v[136:137], off
	v_lshl_add_u64 v[136:137], v[232:233], 0, s[30:31]
	s_mov_b32 m0, s48
	s_nop 0
	global_load_lds_dwordx4 v[136:137], off
	v_lshl_add_u64 v[136:137], v[234:235], 0, s[30:31]
	s_mov_b32 m0, s49
	s_nop 0
	global_load_lds_dwordx4 v[136:137], off
	s_waitcnt vmcnt(8)
	s_waitcnt lgkmcnt(0)
	s_setprio 1
	s_barrier
	v_mfma_f32_16x16x32_bf16 v[62:65], v[132:135], v[198:201], v[62:65]
	v_mfma_f32_16x16x32_bf16 v[58:61], v[166:169], v[198:201], v[58:61]
	v_mfma_f32_16x16x32_bf16 v[46:49], v[132:135], v[206:209], v[46:49]
	v_mfma_f32_16x16x32_bf16 v[42:45], v[166:169], v[206:209], v[42:45]
	v_mfma_f32_16x16x32_bf16 v[30:33], v[132:135], v[214:217], v[30:33]
	v_mfma_f32_16x16x32_bf16 v[26:29], v[166:169], v[214:217], v[26:29]
	v_mfma_f32_16x16x32_bf16 v[14:17], v[132:135], v[222:225], v[14:17]
	v_mfma_f32_16x16x32_bf16 v[10:13], v[166:169], v[222:225], v[10:13]
	v_mfma_f32_16x16x32_bf16 v[62:65], v[158:161], v[202:205], v[62:65]
	v_mfma_f32_16x16x32_bf16 v[58:61], v[170:173], v[202:205], v[58:61]
	v_mfma_f32_16x16x32_bf16 v[46:49], v[158:161], v[210:213], v[46:49]
	v_mfma_f32_16x16x32_bf16 v[42:45], v[170:173], v[210:213], v[42:45]
	v_mfma_f32_16x16x32_bf16 v[30:33], v[158:161], v[218:221], v[30:33]
	v_mfma_f32_16x16x32_bf16 v[26:29], v[170:173], v[218:221], v[26:29]
	v_mfma_f32_16x16x32_bf16 v[14:17], v[158:161], v[226:229], v[14:17]
	v_mfma_f32_16x16x32_bf16 v[10:13], v[170:173], v[226:229], v[10:13]
	s_setprio 0
	s_setprio 1
	v_mfma_f32_16x16x32_bf16 v[54:57], v[182:185], v[198:201], v[54:57]
	v_mfma_f32_16x16x32_bf16 v[50:53], v[190:193], v[198:201], v[50:53]
	v_mfma_f32_16x16x32_bf16 v[38:41], v[182:185], v[206:209], v[38:41]
	v_mfma_f32_16x16x32_bf16 v[34:37], v[190:193], v[206:209], v[34:37]
	v_mfma_f32_16x16x32_bf16 v[22:25], v[182:185], v[214:217], v[22:25]
	v_mfma_f32_16x16x32_bf16 v[18:21], v[190:193], v[214:217], v[18:21]
	v_mfma_f32_16x16x32_bf16 v[6:9], v[182:185], v[222:225], v[6:9]
	v_mfma_f32_16x16x32_bf16 v[2:5], v[190:193], v[222:225], v[2:5]
	v_mfma_f32_16x16x32_bf16 v[54:57], v[186:189], v[202:205], v[54:57]
	v_mfma_f32_16x16x32_bf16 v[50:53], v[194:197], v[202:205], v[50:53]
	v_mfma_f32_16x16x32_bf16 v[38:41], v[186:189], v[210:213], v[38:41]
	v_mfma_f32_16x16x32_bf16 v[34:37], v[194:197], v[210:213], v[34:37]
	v_mfma_f32_16x16x32_bf16 v[22:25], v[186:189], v[218:221], v[22:25]
	v_mfma_f32_16x16x32_bf16 v[18:21], v[194:197], v[218:221], v[18:21]
	v_mfma_f32_16x16x32_bf16 v[6:9], v[186:189], v[226:229], v[6:9]
	v_mfma_f32_16x16x32_bf16 v[2:5], v[194:197], v[226:229], v[2:5]
	s_barrier
	s_setprio 0
	s_add_i32 s63, s63, 2
	s_add_u32 s0, s0, 0x100
	s_addc_u32 s1, s1, 0
	s_add_u32 s61, s61, 0x100
	s_addc_u32 s62, s62, 0
	s_cmp_gt_u32 s63, 29

.LBB0_1565:
	s_add_u32 s16, s16, 0x160080
	s_addc_u32 s17, s17, 0
	s_add_u32 s46, s20, 0x100
	s_addc_u32 s47, s21, 0
	s_mov_b32 s48, -2
	ds_read_b128 v[144:147], v151
	ds_read_b128 v[154:157], v151 offset:1024
	ds_read_b128 v[158:161], v151 offset:2048
	ds_read_b128 v[162:165], v151 offset:3072
	ds_read_b128 v[166:169], v152
	ds_read_b128 v[170:173], v152 offset:1024
	ds_read_b128 v[174:177], v152 offset:2048
	ds_read_b128 v[178:181], v152 offset:3072
	s_add_u32 s20, s16, 0xffea0080
	s_addc_u32 s21, s17, -1
	s_cmpk_eq_i32 s48, 0x54
	s_cselect_b32 s27, s5, s21
	s_cselect_b32 s26, s4, s20
	s_cselect_b32 s21, s15, s47
	s_cselect_b32 s20, s14, s46
	v_lshl_add_u64 v[214:215], s[16:17], 0, v[136:137]
	s_add_i32 m0, s30, 0xc000
	ds_read_b128 v[182:185], v153
	ds_read_b128 v[186:189], v153 offset:1024
	ds_read_b128 v[190:193], v153 offset:2048
	ds_read_b128 v[194:197], v153 offset:3072
	ds_read_b128 v[198:201], v153 offset:4096
	ds_read_b128 v[202:205], v153 offset:5120
	ds_read_b128 v[206:209], v153 offset:6144
	ds_read_b128 v[210:213], v153 offset:7168
	global_load_lds_dwordx4 v[214:215], off
	v_lshl_add_u64 v[214:215], s[16:17], 0, v[138:139]
	s_add_i32 m0, s30, 0xe000
	s_nop 0
	global_load_lds_dwordx4 v[214:215], off
	s_waitcnt vmcnt(8)
	s_waitcnt lgkmcnt(0)
	s_setprio 1
	s_barrier
	v_mfma_f32_16x16x32_bf16 v[124:127], v[144:147], v[182:185], 0
	v_mfma_f32_16x16x32_bf16 v[120:123], v[158:161], v[182:185], 0
	v_mfma_f32_16x16x32_bf16 v[108:111], v[144:147], v[190:193], 0
	v_mfma_f32_16x16x32_bf16 v[104:107], v[158:161], v[190:193], 0
	v_mfma_f32_16x16x32_bf16 v[88:91], v[144:147], v[198:201], 0
	v_mfma_f32_16x16x32_bf16 v[92:95], v[158:161], v[198:201], 0
	v_mfma_f32_16x16x32_bf16 v[72:75], v[144:147], v[206:209], 0
	v_mfma_f32_16x16x32_bf16 v[76:79], v[158:161], v[206:209], 0
	v_mfma_f32_16x16x32_bf16 v[124:127], v[154:157], v[186:189], v[124:127]
	v_mfma_f32_16x16x32_bf16 v[120:123], v[162:165], v[186:189], v[120:123]
	v_mfma_f32_16x16x32_bf16 v[108:111], v[154:157], v[194:197], v[108:111]
	v_mfma_f32_16x16x32_bf16 v[104:107], v[162:165], v[194:197], v[104:107]
	v_mfma_f32_16x16x32_bf16 v[88:91], v[154:157], v[202:205], v[88:91]
	v_mfma_f32_16x16x32_bf16 v[92:95], v[162:165], v[202:205], v[92:95]
	v_mfma_f32_16x16x32_bf16 v[72:75], v[154:157], v[210:213], v[72:75]
	v_mfma_f32_16x16x32_bf16 v[76:79], v[162:165], v[210:213], v[76:79]
	s_setprio 0
	s_setprio 1
	v_mfma_f32_16x16x32_bf16 v[116:119], v[166:169], v[182:185], 0
	v_mfma_f32_16x16x32_bf16 v[112:115], v[174:177], v[182:185], 0
	v_mfma_f32_16x16x32_bf16 v[96:99], v[166:169], v[190:193], 0
	v_mfma_f32_16x16x32_bf16 v[100:103], v[174:177], v[190:193], 0
	v_mfma_f32_16x16x32_bf16 v[80:83], v[166:169], v[198:201], 0
	v_mfma_f32_16x16x32_bf16 v[84:87], v[174:177], v[198:201], 0
	v_mfma_f32_16x16x32_bf16 v[64:67], v[166:169], v[206:209], 0
	v_mfma_f32_16x16x32_bf16 v[68:71], v[174:177], v[206:209], 0
	v_mfma_f32_16x16x32_bf16 v[116:119], v[170:173], v[186:189], v[116:119]
	v_mfma_f32_16x16x32_bf16 v[112:115], v[178:181], v[186:189], v[112:115]
	v_mfma_f32_16x16x32_bf16 v[96:99], v[170:173], v[194:197], v[96:99]
	v_mfma_f32_16x16x32_bf16 v[100:103], v[178:181], v[194:197], v[100:103]
	v_mfma_f32_16x16x32_bf16 v[80:83], v[170:173], v[202:205], v[80:83]
	v_mfma_f32_16x16x32_bf16 v[84:87], v[178:181], v[202:205], v[84:87]
	v_mfma_f32_16x16x32_bf16 v[64:67], v[170:173], v[210:213], v[64:67]
	v_mfma_f32_16x16x32_bf16 v[68:71], v[178:181], v[210:213], v[68:71]
	s_barrier
	s_setprio 0
	s_add_i32 s49, s40, s29
	v_lshl_add_u64 v[214:215], s[20:21], 0, v[130:131]
	s_mov_b32 m0, s49
	ds_read_b128 v[182:185], v153 offset:16384
	ds_read_b128 v[186:189], v153 offset:17408
	ds_read_b128 v[190:193], v153 offset:18432
	ds_read_b128 v[194:197], v153 offset:19456
	ds_read_b128 v[198:201], v153 offset:20480
	ds_read_b128 v[202:205], v153 offset:21504
	ds_read_b128 v[206:209], v153 offset:22528
	ds_read_b128 v[210:213], v153 offset:23552
	global_load_lds_dwordx4 v[214:215], off
	s_add_i32 m0, s49, 0x2000
	s_add_u32 s52, s20, 0x160000
	v_lshl_add_u64 v[216:217], s[20:21], 0, v[134:135]
	s_addc_u32 s53, s21, 0
	s_add_i32 s49, s41, s29
	global_load_lds_dwordx4 v[216:217], off
	v_lshl_add_u64 v[218:219], s[52:53], 0, v[130:131]
	s_mov_b32 m0, s49
	v_lshl_add_u64 v[220:221], s[26:27], 0, v[132:133]
	global_load_lds_dwordx4 v[218:219], off
	v_lshl_add_u64 v[218:219], s[52:53], 0, v[134:135]
	s_add_i32 m0, s49, 0x2000
	s_nop 0
	global_load_lds_dwordx4 v[218:219], off
	v_lshl_add_u64 v[218:219], s[26:27], 0, v[128:129]
	s_mov_b32 m0, s30
	s_nop 0
	global_load_lds_dwordx4 v[218:219], off
	s_mov_b32 m0, s31
	s_nop 0
	global_load_lds_dwordx4 v[220:221], off
	s_waitcnt vmcnt(8)
	s_waitcnt lgkmcnt(0)
	s_setprio 1
	s_barrier
	v_mfma_f32_16x16x32_bf16 v[56:59], v[144:147], v[182:185], 0
	v_mfma_f32_16x16x32_bf16 v[60:63], v[158:161], v[182:185], 0
	v_mfma_f32_16x16x32_bf16 v[40:43], v[144:147], v[190:193], 0
	v_mfma_f32_16x16x32_bf16 v[44:47], v[158:161], v[190:193], 0
	v_mfma_f32_16x16x32_bf16 v[24:27], v[144:147], v[198:201], 0
	v_mfma_f32_16x16x32_bf16 v[28:31], v[158:161], v[198:201], 0
	v_mfma_f32_16x16x32_bf16 v[8:11], v[144:147], v[206:209], 0
	v_mfma_f32_16x16x32_bf16 v[12:15], v[158:161], v[206:209], 0
	v_mfma_f32_16x16x32_bf16 v[56:59], v[154:157], v[186:189], v[56:59]
	v_mfma_f32_16x16x32_bf16 v[60:63], v[162:165], v[186:189], v[60:63]
	v_mfma_f32_16x16x32_bf16 v[40:43], v[154:157], v[194:197], v[40:43]
	v_mfma_f32_16x16x32_bf16 v[44:47], v[162:165], v[194:197], v[44:47]
	v_mfma_f32_16x16x32_bf16 v[24:27], v[154:157], v[202:205], v[24:27]
	v_mfma_f32_16x16x32_bf16 v[28:31], v[162:165], v[202:205], v[28:31]
	v_mfma_f32_16x16x32_bf16 v[8:11], v[154:157], v[210:213], v[8:11]
	v_mfma_f32_16x16x32_bf16 v[12:15], v[162:165], v[210:213], v[12:15]
	s_setprio 0
	s_setprio 1
	v_mfma_f32_16x16x32_bf16 v[48:51], v[166:169], v[182:185], 0
	v_mfma_f32_16x16x32_bf16 v[52:55], v[174:177], v[182:185], 0
	v_mfma_f32_16x16x32_bf16 v[32:35], v[166:169], v[190:193], 0
	v_mfma_f32_16x16x32_bf16 v[36:39], v[174:177], v[190:193], 0
	v_mfma_f32_16x16x32_bf16 v[16:19], v[166:169], v[198:201], 0
	v_mfma_f32_16x16x32_bf16 v[20:23], v[174:177], v[198:201], 0
	v_mfma_f32_16x16x32_bf16 v[0:3], v[166:169], v[206:209], 0
	v_mfma_f32_16x16x32_bf16 v[4:7], v[174:177], v[206:209], 0
	v_mfma_f32_16x16x32_bf16 v[48:51], v[170:173], v[186:189], v[48:51]
	v_mfma_f32_16x16x32_bf16 v[52:55], v[178:181], v[186:189], v[52:55]
	v_mfma_f32_16x16x32_bf16 v[32:35], v[170:173], v[194:197], v[32:35]
	v_mfma_f32_16x16x32_bf16 v[36:39], v[178:181], v[194:197], v[36:39]
	v_mfma_f32_16x16x32_bf16 v[16:19], v[170:173], v[202:205], v[16:19]
	v_mfma_f32_16x16x32_bf16 v[20:23], v[178:181], v[202:205], v[20:23]
	v_mfma_f32_16x16x32_bf16 v[0:3], v[170:173], v[210:213], v[0:3]
	v_mfma_f32_16x16x32_bf16 v[4:7], v[178:181], v[210:213], v[4:7]
	s_barrier
	s_setprio 0
	s_add_i32 s49, 0, 0x18000
	s_add_i32 s52, 0, 0x1c000
	v_add_u32_e32 v162, s49, v149
	v_add_u32_e32 v178, s52, v149
	ds_read_b128 v[144:147], v162
	ds_read_b128 v[154:157], v162 offset:1024
	ds_read_b128 v[158:161], v162 offset:2048
	ds_read_b128 v[162:165], v162 offset:3072
	ds_read_b128 v[166:169], v178
	ds_read_b128 v[170:173], v178 offset:1024
	ds_read_b128 v[174:177], v178 offset:2048
	ds_read_b128 v[178:181], v178 offset:3072
	s_add_u32 s26, s26, 0x160000
	s_addc_u32 s27, s27, 0
	s_mov_b32 m0, s34
	v_lshl_add_u64 v[222:223], s[26:27], 0, v[128:129]
	ds_read_b128 v[182:185], v153 offset:32768
	ds_read_b128 v[186:189], v153 offset:33792
	ds_read_b128 v[190:193], v153 offset:34816
	ds_read_b128 v[194:197], v153 offset:35840
	ds_read_b128 v[198:201], v153 offset:36864
	ds_read_b128 v[202:205], v153 offset:37888
	ds_read_b128 v[206:209], v153 offset:38912
	ds_read_b128 v[210:213], v153 offset:39936
	global_load_lds_dwordx4 v[222:223], off
	v_lshl_add_u64 v[222:223], s[26:27], 0, v[132:133]
	s_mov_b32 m0, s35
	s_nop 0
	global_load_lds_dwordx4 v[222:223], off
	s_waitcnt vmcnt(8)
	s_waitcnt lgkmcnt(0)
	s_setprio 1
	s_barrier
	v_mfma_f32_16x16x32_bf16 v[124:127], v[144:147], v[182:185], v[124:127]
	v_mfma_f32_16x16x32_bf16 v[120:123], v[158:161], v[182:185], v[120:123]
	v_mfma_f32_16x16x32_bf16 v[108:111], v[144:147], v[190:193], v[108:111]
	v_mfma_f32_16x16x32_bf16 v[104:107], v[158:161], v[190:193], v[104:107]
	v_mfma_f32_16x16x32_bf16 v[88:91], v[144:147], v[198:201], v[88:91]
	v_mfma_f32_16x16x32_bf16 v[92:95], v[158:161], v[198:201], v[92:95]
	v_mfma_f32_16x16x32_bf16 v[72:75], v[144:147], v[206:209], v[72:75]
	v_mfma_f32_16x16x32_bf16 v[76:79], v[158:161], v[206:209], v[76:79]
	v_mfma_f32_16x16x32_bf16 v[124:127], v[154:157], v[186:189], v[124:127]
	v_mfma_f32_16x16x32_bf16 v[120:123], v[162:165], v[186:189], v[120:123]
	v_mfma_f32_16x16x32_bf16 v[108:111], v[154:157], v[194:197], v[108:111]
	v_mfma_f32_16x16x32_bf16 v[104:107], v[162:165], v[194:197], v[104:107]
	v_mfma_f32_16x16x32_bf16 v[88:91], v[154:157], v[202:205], v[88:91]
	v_mfma_f32_16x16x32_bf16 v[92:95], v[162:165], v[202:205], v[92:95]
	v_mfma_f32_16x16x32_bf16 v[72:75], v[154:157], v[210:213], v[72:75]
	v_mfma_f32_16x16x32_bf16 v[76:79], v[162:165], v[210:213], v[76:79]
	s_setprio 0
	s_setprio 1
	v_mfma_f32_16x16x32_bf16 v[116:119], v[166:169], v[182:185], v[116:119]
	v_mfma_f32_16x16x32_bf16 v[112:115], v[174:177], v[182:185], v[112:115]
	v_mfma_f32_16x16x32_bf16 v[96:99], v[166:169], v[190:193], v[96:99]
	v_mfma_f32_16x16x32_bf16 v[100:103], v[174:177], v[190:193], v[100:103]
	v_mfma_f32_16x16x32_bf16 v[80:83], v[166:169], v[198:201], v[80:83]
	v_mfma_f32_16x16x32_bf16 v[84:87], v[174:177], v[198:201], v[84:87]
	v_mfma_f32_16x16x32_bf16 v[64:67], v[166:169], v[206:209], v[64:67]
	v_mfma_f32_16x16x32_bf16 v[68:71], v[174:177], v[206:209], v[68:71]
	v_mfma_f32_16x16x32_bf16 v[116:119], v[170:173], v[186:189], v[116:119]
	v_mfma_f32_16x16x32_bf16 v[112:115], v[178:181], v[186:189], v[112:115]
	v_mfma_f32_16x16x32_bf16 v[96:99], v[170:173], v[194:197], v[96:99]
	v_mfma_f32_16x16x32_bf16 v[100:103], v[178:181], v[194:197], v[100:103]
	v_mfma_f32_16x16x32_bf16 v[80:83], v[170:173], v[202:205], v[80:83]
	v_mfma_f32_16x16x32_bf16 v[84:87], v[178:181], v[202:205], v[84:87]
	v_mfma_f32_16x16x32_bf16 v[64:67], v[170:173], v[210:213], v[64:67]
	v_mfma_f32_16x16x32_bf16 v[68:71], v[178:181], v[210:213], v[68:71]
	s_barrier
	s_setprio 0
	s_add_i32 s26, s49, s29
	v_lshl_add_u64 v[214:215], v[214:215], 0, s[8:9]
	s_mov_b32 m0, s26
	ds_read_b128 v[182:185], v153 offset:49152
	ds_read_b128 v[186:189], v153 offset:50176
	ds_read_b128 v[190:193], v153 offset:51200
	ds_read_b128 v[194:197], v153 offset:52224
	ds_read_b128 v[198:201], v153 offset:53248
	ds_read_b128 v[202:205], v153 offset:54272
	ds_read_b128 v[206:209], v153 offset:55296
	ds_read_b128 v[210:213], v153 offset:56320
	global_load_lds_dwordx4 v[214:215], off
	s_add_i32 m0, s26, 0x2000
	s_add_u32 s20, s20, 0x160080
	v_lshl_add_u64 v[214:215], v[216:217], 0, s[8:9]
	s_addc_u32 s21, s21, 0
	s_add_i32 s26, s52, s29
	global_load_lds_dwordx4 v[214:215], off
	v_lshl_add_u64 v[214:215], s[20:21], 0, v[130:131]
	s_mov_b32 m0, s26
	s_nop 0
	global_load_lds_dwordx4 v[214:215], off
	v_lshl_add_u64 v[214:215], s[20:21], 0, v[134:135]
	s_add_i32 m0, s26, 0x2000
	s_nop 0
	global_load_lds_dwordx4 v[214:215], off
	v_lshl_add_u64 v[214:215], v[218:219], 0, s[8:9]
	s_mov_b32 m0, s37
	s_nop 0
	global_load_lds_dwordx4 v[214:215], off
	v_lshl_add_u64 v[214:215], v[220:221], 0, s[8:9]
	s_mov_b32 m0, s38
	s_nop 0
	global_load_lds_dwordx4 v[214:215], off
	s_waitcnt vmcnt(8)
	s_waitcnt lgkmcnt(0)
	s_setprio 1
	s_barrier
	v_mfma_f32_16x16x32_bf16 v[56:59], v[144:147], v[182:185], v[56:59]
	v_mfma_f32_16x16x32_bf16 v[60:63], v[158:161], v[182:185], v[60:63]
	v_mfma_f32_16x16x32_bf16 v[40:43], v[144:147], v[190:193], v[40:43]
	v_mfma_f32_16x16x32_bf16 v[44:47], v[158:161], v[190:193], v[44:47]
	v_mfma_f32_16x16x32_bf16 v[24:27], v[144:147], v[198:201], v[24:27]
	v_mfma_f32_16x16x32_bf16 v[28:31], v[158:161], v[198:201], v[28:31]
	v_mfma_f32_16x16x32_bf16 v[8:11], v[144:147], v[206:209], v[8:11]
	v_mfma_f32_16x16x32_bf16 v[12:15], v[158:161], v[206:209], v[12:15]
	v_mfma_f32_16x16x32_bf16 v[56:59], v[154:157], v[186:189], v[56:59]
	v_mfma_f32_16x16x32_bf16 v[60:63], v[162:165], v[186:189], v[60:63]
	v_mfma_f32_16x16x32_bf16 v[40:43], v[154:157], v[194:197], v[40:43]
	v_mfma_f32_16x16x32_bf16 v[44:47], v[162:165], v[194:197], v[44:47]
	v_mfma_f32_16x16x32_bf16 v[24:27], v[154:157], v[202:205], v[24:27]
	v_mfma_f32_16x16x32_bf16 v[28:31], v[162:165], v[202:205], v[28:31]
	v_mfma_f32_16x16x32_bf16 v[8:11], v[154:157], v[210:213], v[8:11]
	v_mfma_f32_16x16x32_bf16 v[12:15], v[162:165], v[210:213], v[12:15]
	s_setprio 0
	s_setprio 1
	v_mfma_f32_16x16x32_bf16 v[48:51], v[166:169], v[182:185], v[48:51]
	v_mfma_f32_16x16x32_bf16 v[52:55], v[174:177], v[182:185], v[52:55]
	v_mfma_f32_16x16x32_bf16 v[32:35], v[166:169], v[190:193], v[32:35]
	v_mfma_f32_16x16x32_bf16 v[36:39], v[174:177], v[190:193], v[36:39]
	v_mfma_f32_16x16x32_bf16 v[16:19], v[166:169], v[198:201], v[16:19]
	v_mfma_f32_16x16x32_bf16 v[20:23], v[174:177], v[198:201], v[20:23]
	v_mfma_f32_16x16x32_bf16 v[0:3], v[166:169], v[206:209], v[0:3]
	v_mfma_f32_16x16x32_bf16 v[4:7], v[174:177], v[206:209], v[4:7]
	v_mfma_f32_16x16x32_bf16 v[48:51], v[170:173], v[186:189], v[48:51]
	v_mfma_f32_16x16x32_bf16 v[52:55], v[178:181], v[186:189], v[52:55]
	v_mfma_f32_16x16x32_bf16 v[32:35], v[170:173], v[194:197], v[32:35]
	v_mfma_f32_16x16x32_bf16 v[36:39], v[178:181], v[194:197], v[36:39]
	v_mfma_f32_16x16x32_bf16 v[16:19], v[170:173], v[202:205], v[16:19]
	v_mfma_f32_16x16x32_bf16 v[20:23], v[178:181], v[202:205], v[20:23]
	v_mfma_f32_16x16x32_bf16 v[0:3], v[170:173], v[210:213], v[0:3]
	v_mfma_f32_16x16x32_bf16 v[4:7], v[178:181], v[210:213], v[4:7]
	s_barrier
	s_setprio 0
	s_add_i32 s48, s48, 2
	s_add_u32 s16, s16, 0x100
	s_addc_u32 s17, s17, 0
	s_add_u32 s46, s46, 0x100
	s_addc_u32 s47, s47, 0
	s_cmpk_gt_u32 s48, 0x55
